# conv/SiLU loop: window bf16 values read with ds_read_u16_d16_hi into pre-zeroed VGPRs, removing 8 shift conversions per row pair
# speedup vs baseline: 1.0028x; 1.0028x over previous
; DI int glds_row(int i) { const int tid = ltid(); return ((tid >> 6) * 4 + i) * 8 + ((tid & 63) >> 3); }
; DI int glds_chunk(int row) { return (ltid() & 7) ^ ((row >> 1) & 7); }
; DI void phase_up(const Params& P, int layer, char* smem) {
;     ...
;   for (int t0 = blockIdx.x; t0 < MT * NT; t0 += gridDim.x) {
;     const int tl = xcd_tile(t0, MT * NT) - (t0 & 7) * ((MT * NT) >> 3);
;     const int mt = (t0 & 1) * 131 + tl / 11, nt = ((t0 & 7) >> 1) * 11 + tl % 11;
;     const int b = mt / 131, i = mt % 131;
;     const int tb0 = i * 126 - 2;
;     unsigned aoff[4], boff[4];
;     const char* Abase = (const char*)(hn + (size_t)b * S_ * 1024);
;     const unsigned zoff = (unsigned)((P.ws + OFF_ZPAGE) - Abase);
; #pragma unroll
;     for (int q = 0; q < 4; ++q) {
;       const int r = glds_row(q), ch = glds_chunk(r);
;       const int tb = tb0 + r;
;       const bool ok = (tb >= 0) && (tb < S_);
;       aoff[q] = ok ? (unsigned)((tb * 1024 + ch * 8) * 2) : zoff;
;       const int wr = (r < 64) ? (nt * 64 + r) : (DFF + nt * 64 + r - 64);
;       boff[q] = (unsigned)((wr * 1024 + ch * 8) * 2);
;     }
;     f32x16 acc[2][2];
;     gemm_core(smem, 16, Abase, (const char*)wup, aoff, boff, acc);
.LBB0_25:
	s_ashr_i32 s18, s2, 3
	s_and_b32 s19, s18, 0xffffffc0
	s_lshl_b32 s20, s18, 1
	s_bfe_u32 s21, s18, 0x10005
	s_and_b32 s20, s20, 62
	s_or_b32 s19, s21, s19
	s_or_b32 s19, s19, s20
	s_or_b32 s20, s18, 63
	s_cmpk_lt_i32 s20, 0x5a1
	s_cselect_b32 s18, s19, s18
	s_bitcmp1_b32 s2, 0
	s_mul_hi_i32 s20, s18, 0x2e8ba2e9
	s_cselect_b32 s19, 0x83, 0
	s_lshr_b32 s21, s20, 31
	s_ashr_i32 s20, s20, 1
	s_add_i32 s21, s20, s21
	s_add_i32 s20, s21, s19
	s_bfe_u32 s19, s2, 0x20001
	s_mul_i32 s21, s21, 11
	s_mul_i32 s19, s19, 11
	s_sub_i32 s18, s18, s21
	s_add_i32 s21, s18, s19
	s_mul_hi_i32 s18, s20, 0x3e88cb3d
	s_lshr_b32 s19, s18, 31
	s_ashr_i32 s18, s18, 5
	v_mov_b32_e32 v0, v161
	s_add_i32 s68, s18, s19
	s_mul_i32 s18, s68, 0x83
	v_ashrrev_i32_e32 v1, 1, v0
	v_lshrrev_b32_e32 v2, 3, v0
	v_bfe_u32 v0, v0, 3, 3
	s_movk_i32 s3, 0xffe0
	s_sub_i32 s28, s20, s18
	v_and_or_b32 v0, v1, s3, v0
	v_mov_b32_e32 v1, v161
	s_mulk_i32 s28, 0x7e
	s_ashr_i32 s69, s68, 31
	v_bfe_u32 v2, v2, 1, 2
	s_add_i32 s29, s28, -2
	s_lshl_b64 s[22:23], s[68:69], 25
	v_xor_b32_e32 v1, v2, v1
	s_add_u32 s18, s84, s22
	v_lshlrev_b32_e32 v1, 4, v1
	s_addc_u32 s19, s85, s23
	s_sub_i32 s22, 0x1b508000, s22
	s_lshl_b32 s21, s21, 6
	v_add_u32_e32 v2, s29, v0
	v_and_b32_e32 v1, 0x70, v1
	s_movk_i32 s3, 0x4000
	s_add_i32 s23, s21, 0xac0
	v_lshl_or_b32 v3, v2, 11, v1
	v_mov_b32_e32 v4, s22
	v_cmp_gt_u32_e32 vcc, s3, v2
	v_mov_b32_e32 v5, s21
	v_mov_b32_e32 v12, v161
	v_cndmask_b32_e32 v136, v4, v3, vcc
	v_mov_b32_e32 v3, s23
	v_cmp_gt_i32_e32 vcc, 64, v0
	v_lshl_add_u64 v[64:65], s[18:19], 0, v[136:137]
	s_mov_b64 s[4:5], 0x100
	v_cndmask_b32_e32 v2, v3, v5, vcc
	v_add_u32_e32 v0, v2, v0
	v_lshl_or_b32 v76, v0, 11, v1
	v_mov_b32_e32 v0, v161
	s_mov_b64 s[6:7], 0x780
	v_ashrrev_i32_e32 v1, 1, v0
	v_and_b32_e32 v1, 0xffffffe0, v1
	v_bfe_u32 v0, v0, 3, 3
	v_or3_b32 v1, v1, v0, 8
	v_mov_b32_e32 v0, v161
	v_lshrrev_b32_e32 v2, 1, v1
	v_xor_b32_e32 v0, v2, v0
	v_lshlrev_b32_e32 v0, 4, v0
	v_add_u32_e32 v2, s29, v1
	v_and_b32_e32 v6, 0x70, v0
	v_lshl_or_b32 v0, v2, 11, v6
	v_cmp_gt_u32_e32 vcc, s3, v2
	s_nop 1
	v_cndmask_b32_e32 v0, v4, v0, vcc
	v_cmp_gt_i32_e32 vcc, 64, v1
	s_nop 1
	v_cndmask_b32_e32 v2, v3, v5, vcc
	v_add_u32_e32 v1, v2, v1
	v_lshl_or_b32 v77, v1, 11, v6
	v_mov_b32_e32 v1, v161
	s_nop 0
	v_ashrrev_i32_e32 v2, 1, v1
	v_and_b32_e32 v2, 0xffffffe0, v2
	v_lshrrev_b32_e32 v6, 3, v1
	v_bfe_u32 v1, v1, 3, 3
	v_or3_b32 v1, v2, v1, 16
	v_mov_b32_e32 v2, v161
	v_bfe_u32 v6, v6, 1, 2
	v_xor_b32_e32 v2, v6, v2
	v_lshlrev_b32_e32 v2, 4, v2
	v_add_u32_e32 v6, s29, v1
	v_and_b32_e32 v7, 0x70, v2
	v_lshl_or_b32 v2, v6, 11, v7
	v_cmp_gt_u32_e32 vcc, s3, v6
	s_nop 1
	v_cndmask_b32_e32 v2, v4, v2, vcc
	v_cmp_gt_i32_e32 vcc, 64, v1
	s_nop 1
	v_cndmask_b32_e32 v6, v3, v5, vcc
	v_add_u32_e32 v1, v6, v1
	v_lshl_or_b32 v78, v1, 11, v7
	v_mov_b32_e32 v1, v161
	s_nop 0
	v_ashrrev_i32_e32 v6, 1, v1
	v_and_b32_e32 v6, 0xffffffe0, v6
	v_bfe_u32 v1, v1, 3, 3
	v_or3_b32 v1, v6, v1, 24
	v_mov_b32_e32 v6, v161
	v_lshrrev_b32_e32 v7, 1, v1
	v_xor_b32_e32 v6, v7, v6
	v_lshlrev_b32_e32 v6, 4, v6
	v_add_u32_e32 v7, s29, v1
	v_and_b32_e32 v6, 0x70, v6
	v_lshl_or_b32 v8, v7, 11, v6
	v_cmp_gt_u32_e32 vcc, s3, v7
	s_mov_b32 s3, 0x1ffffc0
	v_bfe_u32 v86, v12, 1, 3
	v_cndmask_b32_e32 v4, v4, v8, vcc
	v_cmp_gt_i32_e32 vcc, 64, v1
	v_bfe_u32 v117, v12, 5, 1
	s_nop 0
	v_cndmask_b32_e32 v3, v3, v5, vcc
	v_add_u32_e32 v1, v3, v1
	v_lshl_or_b32 v84, v1, 11, v6
	v_and_b32_e32 v1, 31, v12
	v_lshrrev_b32_e32 v5, 1, v12
	v_and_or_b32 v1, v5, s3, v1
	v_lshlrev_b32_e32 v87, 7, v1
	v_lshlrev_b32_e32 v1, 6, v12
	v_and_b32_e32 v97, 0xfffff000, v1
	v_add_u32_e32 v96, 0x4000, v97
	v_readfirstlane_b32 s84, v97
	s_mov_b32 m0, s84
	v_readfirstlane_b32 s85, v96
	v_or_b32_e32 v98, 0x400, v97
	global_load_lds_dwordx4 v136, s[18:19]
	s_mov_b32 m0, s85
	v_readfirstlane_b32 s86, v98
	v_add_u32_e32 v99, 0x4400, v97
	global_load_lds_dwordx4 v76, s[0:1]
	s_mov_b32 m0, s86
	v_readfirstlane_b32 s87, v99
	v_or_b32_e32 v100, 0x800, v97
	global_load_lds_dwordx4 v0, s[18:19]
	s_mov_b32 m0, s87
	v_readfirstlane_b32 s88, v100
	v_add_u32_e32 v101, 0x4800, v97
	v_lshrrev_b32_e32 v3, 5, v12
	global_load_lds_dwordx4 v77, s[0:1]
	s_mov_b32 m0, s88
	v_readfirstlane_b32 s89, v101
	v_or_b32_e32 v102, 0xc00, v97
	v_bitop3_b32 v3, v3, v86, 1 bitop3:0x6c
	global_load_lds_dwordx4 v2, s[18:19]
	s_mov_b32 m0, s89
	v_readfirstlane_b32 s90, v102
	v_add_u32_e32 v103, 0x4c00, v97
	v_lshlrev_b32_e32 v6, 4, v3
	v_mov_b32_e32 v1, v137
	v_mov_b32_e32 v3, v137
	global_load_lds_dwordx4 v78, s[0:1]
	v_mov_b32_e32 v5, v137
	s_mov_b32 m0, s90
	v_readfirstlane_b32 s91, v103
	v_add_u32_e32 v89, 0x8000, v97
	v_lshl_add_u64 v[66:67], s[18:19], 0, v[0:1]
	v_lshl_add_u64 v[68:69], s[18:19], 0, v[2:3]
	v_lshl_add_u64 v[70:71], s[18:19], 0, v[4:5]
	global_load_lds_dwordx4 v4, s[18:19]
	s_mov_b32 m0, s91
	v_add_u32_e32 v88, 0xc000, v97
	v_readfirstlane_b32 s18, v89
	global_load_lds_dwordx4 v84, s[0:1]
	v_lshl_add_u64 v[0:1], v[64:65], 0, s[94:95]
	s_mov_b32 m0, s18
	v_readfirstlane_b32 s19, v88
	v_add_u32_e32 v90, 0x8400, v97
	global_load_lds_dwordx4 v[0:1], off
	s_mov_b32 m0, s19
	v_readfirstlane_b32 s22, v90
	v_add_u32_e32 v91, 0xc400, v97
	global_load_lds_dwordx4 v76, s[14:15]
	v_lshl_add_u64 v[0:1], v[66:67], 0, s[94:95]
	s_mov_b32 m0, s22
	v_readfirstlane_b32 s23, v91
	v_add_u32_e32 v92, 0x8800, v97
	global_load_lds_dwordx4 v[0:1], off
	s_mov_b32 m0, s23
	v_readfirstlane_b32 s29, v92
	v_add_u32_e32 v93, 0xc800, v97
	global_load_lds_dwordx4 v77, s[14:15]
	v_lshl_add_u64 v[0:1], v[68:69], 0, s[94:95]
	s_mov_b32 m0, s29
	v_readfirstlane_b32 s69, v93
	v_add_u32_e32 v94, 0x8c00, v97
	global_load_lds_dwordx4 v[0:1], off
	s_mov_b32 m0, s69
	v_readfirstlane_b32 s70, v94
	v_add_u32_e32 v95, 0xcc00, v97
	global_load_lds_dwordx4 v78, s[14:15]
	v_lshl_add_u64 v[0:1], v[70:71], 0, s[94:95]
	s_mov_b32 m0, s70
	v_readfirstlane_b32 s71, v95
	global_load_lds_dwordx4 v[0:1], off
	s_mov_b32 m0, s71
	v_or_b32_e32 v79, v87, v6
	global_load_lds_dwordx4 v84, s[14:15]
	s_waitcnt vmcnt(8)
	s_waitcnt vmcnt(8) lgkmcnt(0)
	s_barrier
; #define WAIT_V0() asm volatile("s_waitcnt vmcnt(0)" ::: "memory")
; DI void gemm_core(char* smem, int nk, const char* Ab, const char* Bb, const unsigned (&aoff)[4], const unsigned (&boff)[4],
;                   f32x16 (&acc)[2][2]) {
;     ...
;   stage(0, 0);
;   WAIT_V0();
;   __syncthreads();
;   for (int kt = 0; kt < nk; ++kt) {
;     const int cur = kt & 1;
;     if (kt + 1 < nk) stage(cur ^ 1, kt + 1);
;     const char* sb = smem + cur * STAGE_B;
; #pragma unroll
;     for (int ks = 0; ks < 4; ++ks) {
;       bf16x8 af[2], bfr[2];
; #pragma unroll
;       for (int mb = 0; mb < 2; ++mb) af[mb] = *(const bf16x8*)(sb + a_base + mb * 4096 + xo[ks]);
; #pragma unroll
;       for (int nb = 0; nb < 2; ++nb) bfr[nb] = *(const bf16x8*)(sb + b_base + nb * 4096 + xo[ks]);
; #pragma unroll
;       for (int mb = 0; mb < 2; ++mb)
; #pragma unroll
;         for (int nb = 0; nb < 2; ++nb)
;           acc[mb][nb] = __builtin_amdgcn_mfma_f32_32x32x16_bf16(af[mb], bfr[nb], acc[mb][nb], 0, 0, 0);
;     }
;     WAIT_V0();
;     __syncthreads();
;   }
	ds_read_b128 v[0:3], v79
	v_lshlrev_b32_e32 v4, 7, v12
	v_and_b32_e32 v116, 0x2f80, v4
	v_or_b32_e32 v81, v116, v6
	ds_read_b128 v[4:7], v81 offset:16384
	ds_read_b128 v[8:11], v81 offset:20480
	s_waitcnt lgkmcnt(0)
	v_mfma_f32_32x32x16_bf16 v[48:63], v[0:3], v[4:7], 0
	s_mov_b32 m0, s84
	s_mov_b32 s3, 0xfffffc0
	v_mfma_f32_32x32x16_bf16 v[32:47], v[0:3], v[8:11], 0
	ds_read_b128 v[0:3], v79 offset:4096
	s_waitcnt lgkmcnt(0)
	v_mfma_f32_32x32x16_bf16 v[16:31], v[0:3], v[4:7], 0
	v_bitop3_b32 v4, v117, v86, 2 bitop3:0x36
	v_lshlrev_b32_e32 v82, 4, v4
	v_or_b32_e32 v80, v87, v82
	ds_read_b128 v[104:107], v80
	v_or_b32_e32 v83, v116, v82
	ds_read_b128 v[108:111], v83 offset:16384
	ds_read_b128 v[112:115], v83 offset:20480
	s_waitcnt lgkmcnt(0)
	v_mfma_f32_32x32x16_bf16 v[48:63], v[104:107], v[108:111], v[48:63]
	v_bitop3_b32 v82, v117, v86, 4 bitop3:0x36
	v_lshlrev_b32_e32 v85, 4, v82
	v_or_b32_e32 v82, v87, v85
	v_or_b32_e32 v85, v116, v85
	v_bitop3_b32 v86, v117, v86, 6 bitop3:0x36
	v_mfma_f32_32x32x16_bf16 v[32:47], v[104:107], v[112:115], v[32:47]
	ds_read_b128 v[104:107], v80 offset:4096
	v_mfma_f32_32x32x16_bf16 v[0:15], v[0:3], v[8:11], 0
	s_waitcnt lgkmcnt(0)
	v_mfma_f32_32x32x16_bf16 v[16:31], v[104:107], v[108:111], v[16:31]
	ds_read_b128 v[108:111], v85 offset:16384
	v_mfma_f32_32x32x16_bf16 v[0:15], v[104:107], v[112:115], v[0:15]
	ds_read_b128 v[104:107], v82
	ds_read_b128 v[112:115], v85 offset:20480
	s_waitcnt lgkmcnt(0)
	v_mfma_f32_32x32x16_bf16 v[48:63], v[104:107], v[108:111], v[48:63]
	v_mfma_f32_32x32x16_bf16 v[32:47], v[104:107], v[112:115], v[32:47]
	ds_read_b128 v[104:107], v82 offset:4096
	s_waitcnt lgkmcnt(0)
	v_mfma_f32_32x32x16_bf16 v[16:31], v[104:107], v[108:111], v[16:31]
	v_lshlrev_b32_e32 v108, 4, v86
	v_or_b32_e32 v86, v87, v108
	v_or_b32_e32 v87, v116, v108
	ds_read_b128 v[108:111], v87 offset:16384
	v_mfma_f32_32x32x16_bf16 v[0:15], v[104:107], v[112:115], v[0:15]
	ds_read_b128 v[104:107], v86
	ds_read_b128 v[112:115], v87 offset:20480
	s_waitcnt lgkmcnt(0)
	v_mfma_f32_32x32x16_bf16 v[48:63], v[104:107], v[108:111], v[48:63]
	v_mfma_f32_32x32x16_bf16 v[32:47], v[104:107], v[112:115], v[32:47]
	ds_read_b128 v[104:107], v86 offset:4096
	s_waitcnt vmcnt(0)
	s_waitcnt vmcnt(0) lgkmcnt(0)
	s_barrier
	v_mfma_f32_32x32x16_bf16 v[16:31], v[104:107], v[108:111], v[16:31]
	v_mfma_f32_32x32x16_bf16 v[0:15], v[104:107], v[112:115], v[0:15]
	v_lshl_add_u64 v[104:105], v[64:65], 0, s[4:5]
	global_load_lds_dwordx4 v[104:105], off
	s_mov_b32 m0, s85
	v_lshl_add_u64 v[104:105], v[66:67], 0, s[4:5]
	global_load_lds_dwordx4 v76, s[16:17]
	s_mov_b32 m0, s86
	s_nop 0
	global_load_lds_dwordx4 v[104:105], off
	s_mov_b32 m0, s87
	v_lshl_add_u64 v[104:105], v[68:69], 0, s[4:5]
	global_load_lds_dwordx4 v77, s[16:17]
	s_mov_b32 m0, s88
	s_nop 0
	global_load_lds_dwordx4 v[104:105], off
	s_mov_b32 m0, s89
	v_lshl_add_u64 v[104:105], v[70:71], 0, s[4:5]
	global_load_lds_dwordx4 v78, s[16:17]
	s_mov_b32 m0, s90
	s_mov_b64 s[4:5], 0x180
	global_load_lds_dwordx4 v[104:105], off
	s_mov_b32 m0, s91
	s_nop 0
	global_load_lds_dwordx4 v84, s[16:17]
	ds_read_b128 v[104:107], v79 offset:32768
	ds_read_b128 v[108:111], v81 offset:49152
	ds_read_b128 v[112:115], v81 offset:53248
	s_waitcnt lgkmcnt(0)
	v_mfma_f32_32x32x16_bf16 v[48:63], v[104:107], v[108:111], v[48:63]
	s_mov_b32 m0, s18
	v_mfma_f32_32x32x16_bf16 v[32:47], v[104:107], v[112:115], v[32:47]
	ds_read_b128 v[104:107], v79 offset:36864
	s_waitcnt lgkmcnt(0)
	v_mfma_f32_32x32x16_bf16 v[16:31], v[104:107], v[108:111], v[16:31]
	v_mfma_f32_32x32x16_bf16 v[0:15], v[104:107], v[112:115], v[0:15]
	ds_read_b128 v[104:107], v80 offset:32768
	ds_read_b128 v[108:111], v83 offset:49152
	ds_read_b128 v[112:115], v83 offset:53248
	s_waitcnt lgkmcnt(0)
	v_mfma_f32_32x32x16_bf16 v[48:63], v[104:107], v[108:111], v[48:63]
	v_mfma_f32_32x32x16_bf16 v[32:47], v[104:107], v[112:115], v[32:47]
	ds_read_b128 v[104:107], v80 offset:36864
	s_waitcnt lgkmcnt(0)
	v_mfma_f32_32x32x16_bf16 v[16:31], v[104:107], v[108:111], v[16:31]
	v_mfma_f32_32x32x16_bf16 v[0:15], v[104:107], v[112:115], v[0:15]
	ds_read_b128 v[104:107], v82 offset:32768
	ds_read_b128 v[108:111], v85 offset:49152
	ds_read_b128 v[112:115], v85 offset:53248
	s_waitcnt lgkmcnt(0)
	v_mfma_f32_32x32x16_bf16 v[48:63], v[104:107], v[108:111], v[48:63]
	v_mfma_f32_32x32x16_bf16 v[32:47], v[104:107], v[112:115], v[32:47]
	ds_read_b128 v[104:107], v82 offset:36864
	s_waitcnt lgkmcnt(0)
	v_mfma_f32_32x32x16_bf16 v[16:31], v[104:107], v[108:111], v[16:31]
	v_mfma_f32_32x32x16_bf16 v[0:15], v[104:107], v[112:115], v[0:15]
	ds_read_b128 v[104:107], v86 offset:32768
	ds_read_b128 v[108:111], v87 offset:49152
	ds_read_b128 v[112:115], v87 offset:53248
	s_waitcnt lgkmcnt(0)
	v_mfma_f32_32x32x16_bf16 v[48:63], v[104:107], v[108:111], v[48:63]
	v_mfma_f32_32x32x16_bf16 v[32:47], v[104:107], v[112:115], v[32:47]
	ds_read_b128 v[104:107], v86 offset:36864
	s_waitcnt vmcnt(0)
	s_waitcnt vmcnt(0) lgkmcnt(0)
	s_barrier
; #define WAIT_V0() asm volatile("s_waitcnt vmcnt(0)" ::: "memory")
; DI void gemm_core(char* smem, int nk, const char* Ab, const char* Bb, const unsigned (&aoff)[4], const unsigned (&boff)[4],
;                   f32x16 (&acc)[2][2]) {
;     ...
;   for (int kt = 0; kt < nk; ++kt) {
;     const int cur = kt & 1;
;     if (kt + 1 < nk) stage(cur ^ 1, kt + 1);
;     const char* sb = smem + cur * STAGE_B;
; #pragma unroll
;     for (int ks = 0; ks < 4; ++ks) {
;       bf16x8 af[2], bfr[2];
; #pragma unroll
;       for (int mb = 0; mb < 2; ++mb) af[mb] = *(const bf16x8*)(sb + a_base + mb * 4096 + xo[ks]);
; #pragma unroll
;       for (int nb = 0; nb < 2; ++nb) bfr[nb] = *(const bf16x8*)(sb + b_base + nb * 4096 + xo[ks]);
; #pragma unroll
;       for (int mb = 0; mb < 2; ++mb)
; #pragma unroll
;         for (int nb = 0; nb < 2; ++nb)
;           acc[mb][nb] = __builtin_amdgcn_mfma_f32_32x32x16_bf16(af[mb], bfr[nb], acc[mb][nb], 0, 0, 0);
;     }
;     WAIT_V0();
;     __syncthreads();
;   }
	v_mfma_f32_32x32x16_bf16 v[16:31], v[104:107], v[108:111], v[16:31]
	v_mfma_f32_32x32x16_bf16 v[0:15], v[104:107], v[112:115], v[0:15]
	v_lshl_add_u64 v[104:105], v[64:65], 0, s[4:5]
	global_load_lds_dwordx4 v[104:105], off
	s_mov_b32 m0, s19
	v_lshl_add_u64 v[104:105], v[66:67], 0, s[4:5]
	global_load_lds_dwordx4 v76, s[42:43]
	s_mov_b32 m0, s22
	s_nop 0
	global_load_lds_dwordx4 v[104:105], off
	s_mov_b32 m0, s23
	v_lshl_add_u64 v[104:105], v[68:69], 0, s[4:5]
	global_load_lds_dwordx4 v77, s[42:43]
	s_mov_b32 m0, s29
	s_nop 0
	global_load_lds_dwordx4 v[104:105], off
	s_mov_b32 m0, s69
	v_lshl_add_u64 v[104:105], v[70:71], 0, s[4:5]
	global_load_lds_dwordx4 v78, s[42:43]
	s_mov_b32 m0, s70
	s_mov_b64 s[4:5], 0x280
	global_load_lds_dwordx4 v[104:105], off
	s_mov_b32 m0, s71
	s_nop 0
	global_load_lds_dwordx4 v84, s[42:43]
	ds_read_b128 v[104:107], v79
	ds_read_b128 v[108:111], v81 offset:16384
	ds_read_b128 v[112:115], v81 offset:20480
	s_waitcnt lgkmcnt(0)
	v_mfma_f32_32x32x16_bf16 v[48:63], v[104:107], v[108:111], v[48:63]
	s_mov_b32 m0, s84
	v_mfma_f32_32x32x16_bf16 v[32:47], v[104:107], v[112:115], v[32:47]
	ds_read_b128 v[104:107], v79 offset:4096
	s_waitcnt lgkmcnt(0)
	v_mfma_f32_32x32x16_bf16 v[16:31], v[104:107], v[108:111], v[16:31]
	v_mfma_f32_32x32x16_bf16 v[0:15], v[104:107], v[112:115], v[0:15]
	ds_read_b128 v[104:107], v80
	ds_read_b128 v[108:111], v83 offset:16384
	ds_read_b128 v[112:115], v83 offset:20480
	s_waitcnt lgkmcnt(0)
	v_mfma_f32_32x32x16_bf16 v[48:63], v[104:107], v[108:111], v[48:63]
	v_mfma_f32_32x32x16_bf16 v[32:47], v[104:107], v[112:115], v[32:47]
	ds_read_b128 v[104:107], v80 offset:4096
	s_waitcnt lgkmcnt(0)
	v_mfma_f32_32x32x16_bf16 v[16:31], v[104:107], v[108:111], v[16:31]
	v_mfma_f32_32x32x16_bf16 v[0:15], v[104:107], v[112:115], v[0:15]
	ds_read_b128 v[104:107], v82
	ds_read_b128 v[108:111], v85 offset:16384
	ds_read_b128 v[112:115], v85 offset:20480
	s_waitcnt lgkmcnt(0)
	v_mfma_f32_32x32x16_bf16 v[48:63], v[104:107], v[108:111], v[48:63]
	v_mfma_f32_32x32x16_bf16 v[32:47], v[104:107], v[112:115], v[32:47]
	ds_read_b128 v[104:107], v82 offset:4096
	s_waitcnt lgkmcnt(0)
	v_mfma_f32_32x32x16_bf16 v[16:31], v[104:107], v[108:111], v[16:31]
	v_mfma_f32_32x32x16_bf16 v[0:15], v[104:107], v[112:115], v[0:15]
	ds_read_b128 v[104:107], v86
	ds_read_b128 v[108:111], v87 offset:16384
	ds_read_b128 v[112:115], v87 offset:20480
	s_waitcnt lgkmcnt(0)
	v_mfma_f32_32x32x16_bf16 v[48:63], v[104:107], v[108:111], v[48:63]
	v_mfma_f32_32x32x16_bf16 v[32:47], v[104:107], v[112:115], v[32:47]
	ds_read_b128 v[104:107], v86 offset:4096
	s_waitcnt vmcnt(0)
	s_waitcnt vmcnt(0) lgkmcnt(0)
	s_barrier
	v_mfma_f32_32x32x16_bf16 v[16:31], v[104:107], v[108:111], v[16:31]
	v_mfma_f32_32x32x16_bf16 v[0:15], v[104:107], v[112:115], v[0:15]
	v_lshl_add_u64 v[104:105], v[64:65], 0, s[30:31]
	global_load_lds_dwordx4 v[104:105], off
	s_mov_b32 m0, s85
	v_lshl_add_u64 v[104:105], v[66:67], 0, s[30:31]
	global_load_lds_dwordx4 v76, s[44:45]
	s_mov_b32 m0, s86
	s_nop 0
	global_load_lds_dwordx4 v[104:105], off
	s_mov_b32 m0, s87
	v_lshl_add_u64 v[104:105], v[68:69], 0, s[30:31]
	global_load_lds_dwordx4 v77, s[44:45]
	s_mov_b32 m0, s88
	s_nop 0
	global_load_lds_dwordx4 v[104:105], off
	s_mov_b32 m0, s89
	v_lshl_add_u64 v[104:105], v[70:71], 0, s[30:31]
	global_load_lds_dwordx4 v78, s[44:45]
	s_mov_b32 m0, s90
	s_nop 0
	global_load_lds_dwordx4 v[104:105], off
	s_mov_b32 m0, s91
	s_nop 0
	global_load_lds_dwordx4 v84, s[44:45]
	ds_read_b128 v[104:107], v79 offset:32768
	ds_read_b128 v[108:111], v81 offset:49152
	ds_read_b128 v[112:115], v81 offset:53248
	s_waitcnt lgkmcnt(0)
	v_mfma_f32_32x32x16_bf16 v[48:63], v[104:107], v[108:111], v[48:63]
	s_mov_b32 m0, s18
	v_mfma_f32_32x32x16_bf16 v[32:47], v[104:107], v[112:115], v[32:47]
	ds_read_b128 v[104:107], v79 offset:36864
	s_waitcnt lgkmcnt(0)
	v_mfma_f32_32x32x16_bf16 v[16:31], v[104:107], v[108:111], v[16:31]
	v_mfma_f32_32x32x16_bf16 v[0:15], v[104:107], v[112:115], v[0:15]
	ds_read_b128 v[104:107], v80 offset:32768
	ds_read_b128 v[108:111], v83 offset:49152
	ds_read_b128 v[112:115], v83 offset:53248
	s_waitcnt lgkmcnt(0)
	v_mfma_f32_32x32x16_bf16 v[48:63], v[104:107], v[108:111], v[48:63]
	v_mfma_f32_32x32x16_bf16 v[32:47], v[104:107], v[112:115], v[32:47]
	ds_read_b128 v[104:107], v80 offset:36864
	s_waitcnt lgkmcnt(0)
	v_mfma_f32_32x32x16_bf16 v[16:31], v[104:107], v[108:111], v[16:31]
	v_mfma_f32_32x32x16_bf16 v[0:15], v[104:107], v[112:115], v[0:15]
	ds_read_b128 v[104:107], v82 offset:32768
	ds_read_b128 v[108:111], v85 offset:49152
	ds_read_b128 v[112:115], v85 offset:53248
	s_waitcnt lgkmcnt(0)
	v_mfma_f32_32x32x16_bf16 v[48:63], v[104:107], v[108:111], v[48:63]
	v_mfma_f32_32x32x16_bf16 v[32:47], v[104:107], v[112:115], v[32:47]
	ds_read_b128 v[104:107], v82 offset:36864
	s_waitcnt lgkmcnt(0)
	v_mfma_f32_32x32x16_bf16 v[16:31], v[104:107], v[108:111], v[16:31]
	v_mfma_f32_32x32x16_bf16 v[0:15], v[104:107], v[112:115], v[0:15]
	ds_read_b128 v[104:107], v86 offset:32768
	ds_read_b128 v[108:111], v87 offset:49152
	ds_read_b128 v[112:115], v87 offset:53248
	s_waitcnt lgkmcnt(0)
	v_mfma_f32_32x32x16_bf16 v[48:63], v[104:107], v[108:111], v[48:63]
	v_mfma_f32_32x32x16_bf16 v[32:47], v[104:107], v[112:115], v[32:47]
	ds_read_b128 v[104:107], v86 offset:36864
	s_waitcnt vmcnt(0)
	s_waitcnt vmcnt(0) lgkmcnt(0)
	s_barrier
; #define WAIT_V0() asm volatile("s_waitcnt vmcnt(0)" ::: "memory")
; DI void gemm_core(char* smem, int nk, const char* Ab, const char* Bb, const unsigned (&aoff)[4], const unsigned (&boff)[4],
;                   f32x16 (&acc)[2][2]) {
;     ...
;   for (int kt = 0; kt < nk; ++kt) {
;     const int cur = kt & 1;
;     if (kt + 1 < nk) stage(cur ^ 1, kt + 1);
;     const char* sb = smem + cur * STAGE_B;
; #pragma unroll
;     for (int ks = 0; ks < 4; ++ks) {
;       bf16x8 af[2], bfr[2];
; #pragma unroll
;       for (int mb = 0; mb < 2; ++mb) af[mb] = *(const bf16x8*)(sb + a_base + mb * 4096 + xo[ks]);
; #pragma unroll
;       for (int nb = 0; nb < 2; ++nb) bfr[nb] = *(const bf16x8*)(sb + b_base + nb * 4096 + xo[ks]);
; #pragma unroll
;       for (int mb = 0; mb < 2; ++mb)
; #pragma unroll
;         for (int nb = 0; nb < 2; ++nb)
;           acc[mb][nb] = __builtin_amdgcn_mfma_f32_32x32x16_bf16(af[mb], bfr[nb], acc[mb][nb], 0, 0, 0);
;     }
;     WAIT_V0();
;     __syncthreads();
;   }
	v_mfma_f32_32x32x16_bf16 v[16:31], v[104:107], v[108:111], v[16:31]
	v_mfma_f32_32x32x16_bf16 v[0:15], v[104:107], v[112:115], v[0:15]
	v_lshl_add_u64 v[104:105], v[64:65], 0, s[4:5]
	global_load_lds_dwordx4 v[104:105], off
	s_mov_b32 m0, s19
	v_lshl_add_u64 v[104:105], v[66:67], 0, s[4:5]
	global_load_lds_dwordx4 v76, s[46:47]
	s_mov_b32 m0, s22
	s_nop 0
	global_load_lds_dwordx4 v[104:105], off
	s_mov_b32 m0, s23
	v_lshl_add_u64 v[104:105], v[68:69], 0, s[4:5]
	global_load_lds_dwordx4 v77, s[46:47]
	s_mov_b32 m0, s29
	s_nop 0
	global_load_lds_dwordx4 v[104:105], off
	s_mov_b32 m0, s69
	v_lshl_add_u64 v[104:105], v[70:71], 0, s[4:5]
	global_load_lds_dwordx4 v78, s[46:47]
	s_mov_b32 m0, s70
	s_mov_b64 s[4:5], 0x300
	global_load_lds_dwordx4 v[104:105], off
	s_mov_b32 m0, s71
	s_nop 0
	global_load_lds_dwordx4 v84, s[46:47]
	ds_read_b128 v[104:107], v79
	ds_read_b128 v[108:111], v81 offset:16384
	ds_read_b128 v[112:115], v81 offset:20480
	s_waitcnt lgkmcnt(0)
	v_mfma_f32_32x32x16_bf16 v[48:63], v[104:107], v[108:111], v[48:63]
	s_mov_b32 m0, s84
	v_mfma_f32_32x32x16_bf16 v[32:47], v[104:107], v[112:115], v[32:47]
	ds_read_b128 v[104:107], v79 offset:4096
	s_waitcnt lgkmcnt(0)
	v_mfma_f32_32x32x16_bf16 v[16:31], v[104:107], v[108:111], v[16:31]
	v_mfma_f32_32x32x16_bf16 v[0:15], v[104:107], v[112:115], v[0:15]
	ds_read_b128 v[104:107], v80
	ds_read_b128 v[108:111], v83 offset:16384
	ds_read_b128 v[112:115], v83 offset:20480
	s_waitcnt lgkmcnt(0)
	v_mfma_f32_32x32x16_bf16 v[48:63], v[104:107], v[108:111], v[48:63]
	v_mfma_f32_32x32x16_bf16 v[32:47], v[104:107], v[112:115], v[32:47]
	ds_read_b128 v[104:107], v80 offset:4096
	s_waitcnt lgkmcnt(0)
	v_mfma_f32_32x32x16_bf16 v[16:31], v[104:107], v[108:111], v[16:31]
	v_mfma_f32_32x32x16_bf16 v[0:15], v[104:107], v[112:115], v[0:15]
	ds_read_b128 v[104:107], v82
	ds_read_b128 v[108:111], v85 offset:16384
	ds_read_b128 v[112:115], v85 offset:20480
	s_waitcnt lgkmcnt(0)
	v_mfma_f32_32x32x16_bf16 v[48:63], v[104:107], v[108:111], v[48:63]
	v_mfma_f32_32x32x16_bf16 v[32:47], v[104:107], v[112:115], v[32:47]
	ds_read_b128 v[104:107], v82 offset:4096
	s_waitcnt lgkmcnt(0)
	v_mfma_f32_32x32x16_bf16 v[16:31], v[104:107], v[108:111], v[16:31]
	v_mfma_f32_32x32x16_bf16 v[0:15], v[104:107], v[112:115], v[0:15]
	ds_read_b128 v[104:107], v86
	ds_read_b128 v[108:111], v87 offset:16384
	ds_read_b128 v[112:115], v87 offset:20480
	s_waitcnt lgkmcnt(0)
	v_mfma_f32_32x32x16_bf16 v[48:63], v[104:107], v[108:111], v[48:63]
	v_mfma_f32_32x32x16_bf16 v[32:47], v[104:107], v[112:115], v[32:47]
	ds_read_b128 v[104:107], v86 offset:4096
	s_waitcnt vmcnt(0)
	s_waitcnt vmcnt(0) lgkmcnt(0)
	s_barrier
	v_mfma_f32_32x32x16_bf16 v[16:31], v[104:107], v[108:111], v[16:31]
	v_mfma_f32_32x32x16_bf16 v[0:15], v[104:107], v[112:115], v[0:15]
	v_lshl_add_u64 v[104:105], v[64:65], 0, s[4:5]
	global_load_lds_dwordx4 v[104:105], off
	s_mov_b32 m0, s85
	v_lshl_add_u64 v[104:105], v[66:67], 0, s[4:5]
	global_load_lds_dwordx4 v76, s[48:49]
	s_mov_b32 m0, s86
	s_nop 0
	global_load_lds_dwordx4 v[104:105], off
	s_mov_b32 m0, s87
	v_lshl_add_u64 v[104:105], v[68:69], 0, s[4:5]
	global_load_lds_dwordx4 v77, s[48:49]
	s_mov_b32 m0, s88
	s_nop 0
	global_load_lds_dwordx4 v[104:105], off
	s_mov_b32 m0, s89
	v_lshl_add_u64 v[104:105], v[70:71], 0, s[4:5]
	global_load_lds_dwordx4 v78, s[48:49]
	s_mov_b32 m0, s90
	s_mov_b64 s[4:5], 0x380
	global_load_lds_dwordx4 v[104:105], off
	s_mov_b32 m0, s91
	s_nop 0
	global_load_lds_dwordx4 v84, s[48:49]
	ds_read_b128 v[104:107], v79 offset:32768
	ds_read_b128 v[108:111], v81 offset:49152
	ds_read_b128 v[112:115], v81 offset:53248
	s_waitcnt lgkmcnt(0)
	v_mfma_f32_32x32x16_bf16 v[48:63], v[104:107], v[108:111], v[48:63]
	s_mov_b32 m0, s18
	v_mfma_f32_32x32x16_bf16 v[32:47], v[104:107], v[112:115], v[32:47]
	ds_read_b128 v[104:107], v79 offset:36864
	s_waitcnt lgkmcnt(0)
	v_mfma_f32_32x32x16_bf16 v[16:31], v[104:107], v[108:111], v[16:31]
	v_mfma_f32_32x32x16_bf16 v[0:15], v[104:107], v[112:115], v[0:15]
	ds_read_b128 v[104:107], v80 offset:32768
	ds_read_b128 v[108:111], v83 offset:49152
	ds_read_b128 v[112:115], v83 offset:53248
	s_waitcnt lgkmcnt(0)
	v_mfma_f32_32x32x16_bf16 v[48:63], v[104:107], v[108:111], v[48:63]
	v_mfma_f32_32x32x16_bf16 v[32:47], v[104:107], v[112:115], v[32:47]
	ds_read_b128 v[104:107], v80 offset:36864
	s_waitcnt lgkmcnt(0)
	v_mfma_f32_32x32x16_bf16 v[16:31], v[104:107], v[108:111], v[16:31]
	v_mfma_f32_32x32x16_bf16 v[0:15], v[104:107], v[112:115], v[0:15]
	ds_read_b128 v[104:107], v82 offset:32768
	ds_read_b128 v[108:111], v85 offset:49152
	ds_read_b128 v[112:115], v85 offset:53248
	s_waitcnt lgkmcnt(0)
	v_mfma_f32_32x32x16_bf16 v[48:63], v[104:107], v[108:111], v[48:63]
	v_mfma_f32_32x32x16_bf16 v[32:47], v[104:107], v[112:115], v[32:47]
	ds_read_b128 v[104:107], v82 offset:36864
	s_waitcnt lgkmcnt(0)
	v_mfma_f32_32x32x16_bf16 v[16:31], v[104:107], v[108:111], v[16:31]
	v_mfma_f32_32x32x16_bf16 v[0:15], v[104:107], v[112:115], v[0:15]
	ds_read_b128 v[104:107], v86 offset:32768
	ds_read_b128 v[108:111], v87 offset:49152
	ds_read_b128 v[112:115], v87 offset:53248
	s_waitcnt lgkmcnt(0)
	v_mfma_f32_32x32x16_bf16 v[48:63], v[104:107], v[108:111], v[48:63]
	v_mfma_f32_32x32x16_bf16 v[32:47], v[104:107], v[112:115], v[32:47]
	ds_read_b128 v[104:107], v86 offset:36864
	s_waitcnt vmcnt(0)
	s_waitcnt vmcnt(0) lgkmcnt(0)
	s_barrier
; #define WAIT_V0() asm volatile("s_waitcnt vmcnt(0)" ::: "memory")
; DI void gemm_core(char* smem, int nk, const char* Ab, const char* Bb, const unsigned (&aoff)[4], const unsigned (&boff)[4],
;                   f32x16 (&acc)[2][2]) {
;     ...
;   for (int kt = 0; kt < nk; ++kt) {
;     const int cur = kt & 1;
;     if (kt + 1 < nk) stage(cur ^ 1, kt + 1);
;     const char* sb = smem + cur * STAGE_B;
; #pragma unroll
;     for (int ks = 0; ks < 4; ++ks) {
;       bf16x8 af[2], bfr[2];
; #pragma unroll
;       for (int mb = 0; mb < 2; ++mb) af[mb] = *(const bf16x8*)(sb + a_base + mb * 4096 + xo[ks]);
; #pragma unroll
;       for (int nb = 0; nb < 2; ++nb) bfr[nb] = *(const bf16x8*)(sb + b_base + nb * 4096 + xo[ks]);
; #pragma unroll
;       for (int mb = 0; mb < 2; ++mb)
; #pragma unroll
;         for (int nb = 0; nb < 2; ++nb)
;           acc[mb][nb] = __builtin_amdgcn_mfma_f32_32x32x16_bf16(af[mb], bfr[nb], acc[mb][nb], 0, 0, 0);
;     }
;     WAIT_V0();
;     __syncthreads();
;   }
	v_mfma_f32_32x32x16_bf16 v[16:31], v[104:107], v[108:111], v[16:31]
	v_mfma_f32_32x32x16_bf16 v[0:15], v[104:107], v[112:115], v[0:15]
	v_lshl_add_u64 v[104:105], v[64:65], 0, s[4:5]
	global_load_lds_dwordx4 v[104:105], off
	s_mov_b32 m0, s19
	v_lshl_add_u64 v[104:105], v[66:67], 0, s[4:5]
	global_load_lds_dwordx4 v76, s[50:51]
	s_mov_b32 m0, s22
	s_nop 0
	global_load_lds_dwordx4 v[104:105], off
	s_mov_b32 m0, s23
	v_lshl_add_u64 v[104:105], v[68:69], 0, s[4:5]
	global_load_lds_dwordx4 v77, s[50:51]
	s_mov_b32 m0, s29
	s_nop 0
	global_load_lds_dwordx4 v[104:105], off
	s_mov_b32 m0, s69
	v_lshl_add_u64 v[104:105], v[70:71], 0, s[4:5]
	global_load_lds_dwordx4 v78, s[50:51]
	s_mov_b32 m0, s70
	s_mov_b64 s[4:5], 0x400
	global_load_lds_dwordx4 v[104:105], off
	s_mov_b32 m0, s71
	s_nop 0
	global_load_lds_dwordx4 v84, s[50:51]
	ds_read_b128 v[104:107], v79
	ds_read_b128 v[108:111], v81 offset:16384
	ds_read_b128 v[112:115], v81 offset:20480
	s_waitcnt lgkmcnt(0)
	v_mfma_f32_32x32x16_bf16 v[48:63], v[104:107], v[108:111], v[48:63]
	s_mov_b32 m0, s84
	v_readfirstlane_b32 s84, v89
	v_mfma_f32_32x32x16_bf16 v[32:47], v[104:107], v[112:115], v[32:47]
	ds_read_b128 v[104:107], v79 offset:4096
	s_waitcnt lgkmcnt(0)
	v_mfma_f32_32x32x16_bf16 v[16:31], v[104:107], v[108:111], v[16:31]
	v_mfma_f32_32x32x16_bf16 v[0:15], v[104:107], v[112:115], v[0:15]
	ds_read_b128 v[104:107], v80
	ds_read_b128 v[108:111], v83 offset:16384
	ds_read_b128 v[112:115], v83 offset:20480
	s_waitcnt lgkmcnt(0)
	v_mfma_f32_32x32x16_bf16 v[48:63], v[104:107], v[108:111], v[48:63]
	v_mfma_f32_32x32x16_bf16 v[32:47], v[104:107], v[112:115], v[32:47]
	ds_read_b128 v[104:107], v80 offset:4096
	s_waitcnt lgkmcnt(0)
	v_mfma_f32_32x32x16_bf16 v[16:31], v[104:107], v[108:111], v[16:31]
	v_mfma_f32_32x32x16_bf16 v[0:15], v[104:107], v[112:115], v[0:15]
	ds_read_b128 v[104:107], v82
	ds_read_b128 v[108:111], v85 offset:16384
	ds_read_b128 v[112:115], v85 offset:20480
	s_waitcnt lgkmcnt(0)
	v_mfma_f32_32x32x16_bf16 v[48:63], v[104:107], v[108:111], v[48:63]
	v_mfma_f32_32x32x16_bf16 v[32:47], v[104:107], v[112:115], v[32:47]
	ds_read_b128 v[104:107], v82 offset:4096
	s_waitcnt lgkmcnt(0)
	v_mfma_f32_32x32x16_bf16 v[16:31], v[104:107], v[108:111], v[16:31]
	v_mfma_f32_32x32x16_bf16 v[0:15], v[104:107], v[112:115], v[0:15]
	ds_read_b128 v[104:107], v86
	ds_read_b128 v[108:111], v87 offset:16384
	ds_read_b128 v[112:115], v87 offset:20480
	s_waitcnt lgkmcnt(0)
	v_mfma_f32_32x32x16_bf16 v[48:63], v[104:107], v[108:111], v[48:63]
	v_mfma_f32_32x32x16_bf16 v[32:47], v[104:107], v[112:115], v[32:47]
	ds_read_b128 v[104:107], v86 offset:4096
	s_waitcnt vmcnt(0)
	s_waitcnt vmcnt(0) lgkmcnt(0)
	s_barrier
	v_mfma_f32_32x32x16_bf16 v[16:31], v[104:107], v[108:111], v[16:31]
	v_mfma_f32_32x32x16_bf16 v[0:15], v[104:107], v[112:115], v[0:15]
	v_lshl_add_u64 v[104:105], v[64:65], 0, s[4:5]
	global_load_lds_dwordx4 v[104:105], off
	s_mov_b32 m0, s85
	v_lshl_add_u64 v[104:105], v[66:67], 0, s[4:5]
	global_load_lds_dwordx4 v76, s[52:53]
	s_mov_b32 m0, s86
	v_readfirstlane_b32 s85, v88
	global_load_lds_dwordx4 v[104:105], off
	s_mov_b32 m0, s87
	v_lshl_add_u64 v[104:105], v[68:69], 0, s[4:5]
	global_load_lds_dwordx4 v77, s[52:53]
	s_mov_b32 m0, s88
	v_readfirstlane_b32 s86, v90
	global_load_lds_dwordx4 v[104:105], off
	s_mov_b32 m0, s89
	v_lshl_add_u64 v[104:105], v[70:71], 0, s[4:5]
	global_load_lds_dwordx4 v78, s[52:53]
	s_mov_b32 m0, s90
	s_mov_b64 s[4:5], 0x480
	global_load_lds_dwordx4 v[104:105], off
	s_mov_b32 m0, s91
	v_readfirstlane_b32 s87, v91
	global_load_lds_dwordx4 v84, s[52:53]
	ds_read_b128 v[104:107], v79 offset:32768
	ds_read_b128 v[108:111], v81 offset:49152
	ds_read_b128 v[112:115], v81 offset:53248
	s_waitcnt lgkmcnt(0)
	v_mfma_f32_32x32x16_bf16 v[48:63], v[104:107], v[108:111], v[48:63]
	s_mov_b32 m0, s18
	v_readfirstlane_b32 s18, v97
	v_readfirstlane_b32 s88, v92
	v_readfirstlane_b32 s89, v93
	v_readfirstlane_b32 s90, v94
	v_readfirstlane_b32 s91, v95
	v_mfma_f32_32x32x16_bf16 v[32:47], v[104:107], v[112:115], v[32:47]
	ds_read_b128 v[104:107], v79 offset:36864
	s_waitcnt lgkmcnt(0)
	v_mfma_f32_32x32x16_bf16 v[16:31], v[104:107], v[108:111], v[16:31]
	v_mfma_f32_32x32x16_bf16 v[0:15], v[104:107], v[112:115], v[0:15]
	ds_read_b128 v[104:107], v80 offset:32768
	ds_read_b128 v[108:111], v83 offset:49152
	ds_read_b128 v[112:115], v83 offset:53248
	s_waitcnt lgkmcnt(0)
	v_mfma_f32_32x32x16_bf16 v[48:63], v[104:107], v[108:111], v[48:63]
	v_mfma_f32_32x32x16_bf16 v[32:47], v[104:107], v[112:115], v[32:47]
	ds_read_b128 v[104:107], v80 offset:36864
	s_waitcnt lgkmcnt(0)
	v_mfma_f32_32x32x16_bf16 v[16:31], v[104:107], v[108:111], v[16:31]
	v_mfma_f32_32x32x16_bf16 v[0:15], v[104:107], v[112:115], v[0:15]
	ds_read_b128 v[104:107], v82 offset:32768
	ds_read_b128 v[108:111], v85 offset:49152
	ds_read_b128 v[112:115], v85 offset:53248
	s_waitcnt lgkmcnt(0)
	v_mfma_f32_32x32x16_bf16 v[48:63], v[104:107], v[108:111], v[48:63]
	v_mfma_f32_32x32x16_bf16 v[32:47], v[104:107], v[112:115], v[32:47]
	ds_read_b128 v[104:107], v82 offset:36864
	s_waitcnt lgkmcnt(0)
	v_mfma_f32_32x32x16_bf16 v[16:31], v[104:107], v[108:111], v[16:31]
	v_mfma_f32_32x32x16_bf16 v[0:15], v[104:107], v[112:115], v[0:15]
	ds_read_b128 v[104:107], v86 offset:32768
	ds_read_b128 v[108:111], v87 offset:49152
	ds_read_b128 v[112:115], v87 offset:53248
	s_waitcnt lgkmcnt(0)
	v_mfma_f32_32x32x16_bf16 v[48:63], v[104:107], v[108:111], v[48:63]
	v_mfma_f32_32x32x16_bf16 v[32:47], v[104:107], v[112:115], v[32:47]
	ds_read_b128 v[104:107], v86 offset:36864
	s_waitcnt vmcnt(0)
	s_waitcnt vmcnt(0) lgkmcnt(0)
	s_barrier
; #define WAIT_V0() asm volatile("s_waitcnt vmcnt(0)" ::: "memory")
; DI void gemm_core(char* smem, int nk, const char* Ab, const char* Bb, const unsigned (&aoff)[4], const unsigned (&boff)[4],
;                   f32x16 (&acc)[2][2]) {
;     ...
;   for (int kt = 0; kt < nk; ++kt) {
;     const int cur = kt & 1;
;     if (kt + 1 < nk) stage(cur ^ 1, kt + 1);
;     const char* sb = smem + cur * STAGE_B;
; #pragma unroll
;     for (int ks = 0; ks < 4; ++ks) {
;       bf16x8 af[2], bfr[2];
; #pragma unroll
;       for (int mb = 0; mb < 2; ++mb) af[mb] = *(const bf16x8*)(sb + a_base + mb * 4096 + xo[ks]);
; #pragma unroll
;       for (int nb = 0; nb < 2; ++nb) bfr[nb] = *(const bf16x8*)(sb + b_base + nb * 4096 + xo[ks]);
; #pragma unroll
;       for (int mb = 0; mb < 2; ++mb)
; #pragma unroll
;         for (int nb = 0; nb < 2; ++nb)
;           acc[mb][nb] = __builtin_amdgcn_mfma_f32_32x32x16_bf16(af[mb], bfr[nb], acc[mb][nb], 0, 0, 0);
;     }
;     WAIT_V0();
;     __syncthreads();
;   }
	v_mfma_f32_32x32x16_bf16 v[16:31], v[104:107], v[108:111], v[16:31]
	v_mfma_f32_32x32x16_bf16 v[0:15], v[104:107], v[112:115], v[0:15]
	v_lshl_add_u64 v[104:105], v[64:65], 0, s[4:5]
	global_load_lds_dwordx4 v[104:105], off
	s_mov_b32 m0, s19
	v_lshl_add_u64 v[104:105], v[66:67], 0, s[4:5]
	global_load_lds_dwordx4 v76, s[54:55]
	s_mov_b32 m0, s22
	v_readfirstlane_b32 s19, v96
	global_load_lds_dwordx4 v[104:105], off
	s_mov_b32 m0, s23
	v_lshl_add_u64 v[104:105], v[68:69], 0, s[4:5]
	global_load_lds_dwordx4 v77, s[54:55]
	s_mov_b32 m0, s29
	v_readfirstlane_b32 s22, v98
	global_load_lds_dwordx4 v[104:105], off
	s_mov_b32 m0, s69
	v_lshl_add_u64 v[104:105], v[70:71], 0, s[4:5]
	global_load_lds_dwordx4 v78, s[54:55]
	s_mov_b32 m0, s70
	s_mov_b64 s[4:5], 0x500
	global_load_lds_dwordx4 v[104:105], off
	s_mov_b32 m0, s71
	v_lshl_add_u64 v[96:97], v[66:67], 0, s[4:5]
	global_load_lds_dwordx4 v84, s[54:55]
	ds_read_b128 v[104:107], v79
	ds_read_b128 v[108:111], v81 offset:16384
	ds_read_b128 v[112:115], v81 offset:20480
	s_waitcnt lgkmcnt(0)
	v_mfma_f32_32x32x16_bf16 v[48:63], v[104:107], v[108:111], v[48:63]
	s_mov_b32 m0, s18
	v_readfirstlane_b32 s23, v99
	v_readfirstlane_b32 s29, v100
	v_readfirstlane_b32 s69, v101
	v_readfirstlane_b32 s70, v102
	v_readfirstlane_b32 s71, v103
	v_mfma_f32_32x32x16_bf16 v[32:47], v[104:107], v[112:115], v[32:47]
	ds_read_b128 v[104:107], v79 offset:4096
	s_waitcnt lgkmcnt(0)
	v_mfma_f32_32x32x16_bf16 v[16:31], v[104:107], v[108:111], v[16:31]
	v_mfma_f32_32x32x16_bf16 v[0:15], v[104:107], v[112:115], v[0:15]
	ds_read_b128 v[104:107], v80
	ds_read_b128 v[108:111], v83 offset:16384
	ds_read_b128 v[112:115], v83 offset:20480
	s_waitcnt lgkmcnt(0)
	v_mfma_f32_32x32x16_bf16 v[48:63], v[104:107], v[108:111], v[48:63]
	v_mfma_f32_32x32x16_bf16 v[32:47], v[104:107], v[112:115], v[32:47]
	ds_read_b128 v[104:107], v80 offset:4096
	s_waitcnt lgkmcnt(0)
	v_mfma_f32_32x32x16_bf16 v[16:31], v[104:107], v[108:111], v[16:31]
	v_mfma_f32_32x32x16_bf16 v[0:15], v[104:107], v[112:115], v[0:15]
	ds_read_b128 v[104:107], v82
	ds_read_b128 v[108:111], v85 offset:16384
	ds_read_b128 v[112:115], v85 offset:20480
	s_waitcnt lgkmcnt(0)
	v_mfma_f32_32x32x16_bf16 v[48:63], v[104:107], v[108:111], v[48:63]
	v_mfma_f32_32x32x16_bf16 v[32:47], v[104:107], v[112:115], v[32:47]
	ds_read_b128 v[104:107], v82 offset:4096
	s_waitcnt lgkmcnt(0)
	v_mfma_f32_32x32x16_bf16 v[16:31], v[104:107], v[108:111], v[16:31]
	v_mfma_f32_32x32x16_bf16 v[0:15], v[104:107], v[112:115], v[0:15]
	ds_read_b128 v[104:107], v86
	ds_read_b128 v[108:111], v87 offset:16384
	ds_read_b128 v[112:115], v87 offset:20480
	s_waitcnt lgkmcnt(0)
	v_mfma_f32_32x32x16_bf16 v[48:63], v[104:107], v[108:111], v[48:63]
	v_mfma_f32_32x32x16_bf16 v[32:47], v[104:107], v[112:115], v[32:47]
	ds_read_b128 v[104:107], v86 offset:4096
	s_waitcnt vmcnt(0)
	s_waitcnt vmcnt(0) lgkmcnt(0)
	s_barrier
	v_mfma_f32_32x32x16_bf16 v[16:31], v[104:107], v[108:111], v[16:31]
	v_mfma_f32_32x32x16_bf16 v[0:15], v[104:107], v[112:115], v[0:15]
	v_lshl_add_u64 v[104:105], v[64:65], 0, s[4:5]
	global_load_lds_dwordx4 v[104:105], off
	s_mov_b32 m0, s19
	s_nop 0
	global_load_lds_dwordx4 v76, s[56:57]
	s_mov_b32 m0, s22
	s_nop 0
	global_load_lds_dwordx4 v[96:97], off
	s_mov_b32 m0, s23
	v_lshl_add_u64 v[96:97], v[68:69], 0, s[4:5]
	global_load_lds_dwordx4 v77, s[56:57]
	s_mov_b32 m0, s29
	s_nop 0
	global_load_lds_dwordx4 v[96:97], off
	s_mov_b32 m0, s69
	v_lshl_add_u64 v[96:97], v[70:71], 0, s[4:5]
	global_load_lds_dwordx4 v78, s[56:57]
	s_mov_b32 m0, s70
	s_mov_b64 s[4:5], 0x580
	global_load_lds_dwordx4 v[96:97], off
	s_mov_b32 m0, s71
	v_lshl_add_u64 v[88:89], v[66:67], 0, s[4:5]
	global_load_lds_dwordx4 v84, s[56:57]
	ds_read_b128 v[96:99], v79 offset:32768
	ds_read_b128 v[100:103], v81 offset:49152
	ds_read_b128 v[104:107], v81 offset:53248
	s_waitcnt lgkmcnt(0)
	v_mfma_f32_32x32x16_bf16 v[48:63], v[96:99], v[100:103], v[48:63]
	s_mov_b32 m0, s84
	v_mfma_f32_32x32x16_bf16 v[32:47], v[96:99], v[104:107], v[32:47]
	ds_read_b128 v[96:99], v79 offset:36864
	s_waitcnt lgkmcnt(0)
	v_mfma_f32_32x32x16_bf16 v[16:31], v[96:99], v[100:103], v[16:31]
	v_mfma_f32_32x32x16_bf16 v[0:15], v[96:99], v[104:107], v[0:15]
	ds_read_b128 v[96:99], v80 offset:32768
	ds_read_b128 v[100:103], v83 offset:49152
	ds_read_b128 v[104:107], v83 offset:53248
	s_waitcnt lgkmcnt(0)
	v_mfma_f32_32x32x16_bf16 v[48:63], v[96:99], v[100:103], v[48:63]
	v_mfma_f32_32x32x16_bf16 v[32:47], v[96:99], v[104:107], v[32:47]
	ds_read_b128 v[96:99], v80 offset:36864
	s_waitcnt lgkmcnt(0)
	v_mfma_f32_32x32x16_bf16 v[16:31], v[96:99], v[100:103], v[16:31]
	v_mfma_f32_32x32x16_bf16 v[0:15], v[96:99], v[104:107], v[0:15]
	ds_read_b128 v[96:99], v82 offset:32768
	ds_read_b128 v[100:103], v85 offset:49152
	ds_read_b128 v[104:107], v85 offset:53248
	s_waitcnt lgkmcnt(0)
	v_mfma_f32_32x32x16_bf16 v[48:63], v[96:99], v[100:103], v[48:63]
	v_mfma_f32_32x32x16_bf16 v[32:47], v[96:99], v[104:107], v[32:47]
	ds_read_b128 v[96:99], v82 offset:36864
	s_waitcnt lgkmcnt(0)
	v_mfma_f32_32x32x16_bf16 v[16:31], v[96:99], v[100:103], v[16:31]
	v_mfma_f32_32x32x16_bf16 v[0:15], v[96:99], v[104:107], v[0:15]
	ds_read_b128 v[96:99], v86 offset:32768
	ds_read_b128 v[100:103], v87 offset:49152
	ds_read_b128 v[104:107], v87 offset:53248
	s_waitcnt lgkmcnt(0)
	v_mfma_f32_32x32x16_bf16 v[48:63], v[96:99], v[100:103], v[48:63]
	v_mfma_f32_32x32x16_bf16 v[32:47], v[96:99], v[104:107], v[32:47]
	ds_read_b128 v[96:99], v86 offset:36864
	s_waitcnt vmcnt(0)
	s_waitcnt vmcnt(0) lgkmcnt(0)
	s_barrier
; #define WAIT_V0() asm volatile("s_waitcnt vmcnt(0)" ::: "memory")
; DI void gemm_core(char* smem, int nk, const char* Ab, const char* Bb, const unsigned (&aoff)[4], const unsigned (&boff)[4],
;                   f32x16 (&acc)[2][2]) {
;     ...
;   auto stage = [&](int buf, int kt) __attribute__((always_inline)) {
;     const char* ak = Ab + kt * 128;
;     const char* bk = Bb + kt * 128;
;     char* sa = smem + buf * STAGE_B + w * 4096;
; #pragma unroll
;     for (int i = 0; i < 4; ++i) {
;       __builtin_amdgcn_global_load_lds((const unsigned*)(ak + aoff[i]), (unsigned*)(sa + i * 1024), 16, 0, 0);
;       __builtin_amdgcn_global_load_lds((const unsigned*)(bk + boff[i]), (unsigned*)(sa + 16384 + i * 1024), 16, 0, 0);
;     }
;   };
;     ...
;   for (int kt = 0; kt < nk; ++kt) {
;     const int cur = kt & 1;
;     if (kt + 1 < nk) stage(cur ^ 1, kt + 1);
;     const char* sb = smem + cur * STAGE_B;
; #pragma unroll
;     for (int ks = 0; ks < 4; ++ks) {
;       bf16x8 af[2], bfr[2];
; #pragma unroll
;       for (int mb = 0; mb < 2; ++mb) af[mb] = *(const bf16x8*)(sb + a_base + mb * 4096 + xo[ks]);
; #pragma unroll
;       for (int nb = 0; nb < 2; ++nb) bfr[nb] = *(const bf16x8*)(sb + b_base + nb * 4096 + xo[ks]);
; #pragma unroll
;       for (int mb = 0; mb < 2; ++mb)
; #pragma unroll
;         for (int nb = 0; nb < 2; ++nb)
;           acc[mb][nb] = __builtin_amdgcn_mfma_f32_32x32x16_bf16(af[mb], bfr[nb], acc[mb][nb], 0, 0, 0);
;     }
;     WAIT_V0();
;     __syncthreads();
;   }
	v_mfma_f32_32x32x16_bf16 v[16:31], v[96:99], v[100:103], v[16:31]
	v_mfma_f32_32x32x16_bf16 v[0:15], v[96:99], v[104:107], v[0:15]
	v_lshl_add_u64 v[96:97], v[64:65], 0, s[4:5]
	global_load_lds_dwordx4 v[96:97], off
	s_mov_b32 m0, s85
	s_nop 0
	global_load_lds_dwordx4 v76, s[58:59]
	s_mov_b32 m0, s86
	s_nop 0
	global_load_lds_dwordx4 v[88:89], off
	s_mov_b32 m0, s87
	v_lshl_add_u64 v[88:89], v[68:69], 0, s[4:5]
	global_load_lds_dwordx4 v77, s[58:59]
	s_mov_b32 m0, s88
	s_nop 0
	global_load_lds_dwordx4 v[88:89], off
	s_mov_b32 m0, s89
	v_lshl_add_u64 v[88:89], v[70:71], 0, s[4:5]
	global_load_lds_dwordx4 v78, s[58:59]
	s_mov_b32 m0, s90
	s_mov_b64 s[4:5], 0x600
	global_load_lds_dwordx4 v[88:89], off
	s_mov_b32 m0, s91
	s_nop 0
	global_load_lds_dwordx4 v84, s[58:59]
	ds_read_b128 v[88:91], v79
	ds_read_b128 v[92:95], v81 offset:16384
	ds_read_b128 v[96:99], v81 offset:20480
	s_waitcnt lgkmcnt(0)
	v_mfma_f32_32x32x16_bf16 v[48:63], v[88:91], v[92:95], v[48:63]
	s_mov_b32 m0, s18
	v_mfma_f32_32x32x16_bf16 v[32:47], v[88:91], v[96:99], v[32:47]
	ds_read_b128 v[88:91], v79 offset:4096
	s_waitcnt lgkmcnt(0)
	v_mfma_f32_32x32x16_bf16 v[16:31], v[88:91], v[92:95], v[16:31]
	v_mfma_f32_32x32x16_bf16 v[0:15], v[88:91], v[96:99], v[0:15]
	ds_read_b128 v[88:91], v80
	ds_read_b128 v[92:95], v83 offset:16384
	ds_read_b128 v[96:99], v83 offset:20480
	s_waitcnt lgkmcnt(0)
	v_mfma_f32_32x32x16_bf16 v[48:63], v[88:91], v[92:95], v[48:63]
	v_mfma_f32_32x32x16_bf16 v[32:47], v[88:91], v[96:99], v[32:47]
	ds_read_b128 v[88:91], v80 offset:4096
	s_waitcnt lgkmcnt(0)
	v_mfma_f32_32x32x16_bf16 v[16:31], v[88:91], v[92:95], v[16:31]
	v_mfma_f32_32x32x16_bf16 v[0:15], v[88:91], v[96:99], v[0:15]
	ds_read_b128 v[88:91], v82
	ds_read_b128 v[92:95], v85 offset:16384
	ds_read_b128 v[96:99], v85 offset:20480
	s_waitcnt lgkmcnt(0)
	v_mfma_f32_32x32x16_bf16 v[48:63], v[88:91], v[92:95], v[48:63]
	v_mfma_f32_32x32x16_bf16 v[32:47], v[88:91], v[96:99], v[32:47]
	ds_read_b128 v[88:91], v82 offset:4096
	s_waitcnt lgkmcnt(0)
	v_mfma_f32_32x32x16_bf16 v[16:31], v[88:91], v[92:95], v[16:31]
	v_mfma_f32_32x32x16_bf16 v[0:15], v[88:91], v[96:99], v[0:15]
	ds_read_b128 v[88:91], v86
	ds_read_b128 v[92:95], v87 offset:16384
	ds_read_b128 v[96:99], v87 offset:20480
	s_waitcnt lgkmcnt(0)
	v_mfma_f32_32x32x16_bf16 v[48:63], v[88:91], v[92:95], v[48:63]
	v_mfma_f32_32x32x16_bf16 v[32:47], v[88:91], v[96:99], v[32:47]
	ds_read_b128 v[88:91], v86 offset:4096
	s_waitcnt vmcnt(0)
	s_waitcnt vmcnt(0) lgkmcnt(0)
	s_barrier
	v_mfma_f32_32x32x16_bf16 v[16:31], v[88:91], v[92:95], v[16:31]
	v_mfma_f32_32x32x16_bf16 v[0:15], v[88:91], v[96:99], v[0:15]
	v_lshl_add_u64 v[88:89], v[64:65], 0, s[4:5]
	global_load_lds_dwordx4 v[88:89], off
	s_mov_b32 m0, s19
	v_lshl_add_u64 v[88:89], v[66:67], 0, s[4:5]
	global_load_lds_dwordx4 v76, s[60:61]
	s_mov_b32 m0, s22
	s_nop 0
	global_load_lds_dwordx4 v[88:89], off
	s_mov_b32 m0, s23
	v_lshl_add_u64 v[88:89], v[68:69], 0, s[4:5]
	global_load_lds_dwordx4 v77, s[60:61]
	s_mov_b32 m0, s29
	s_nop 0
	global_load_lds_dwordx4 v[88:89], off
	s_mov_b32 m0, s69
	v_lshl_add_u64 v[88:89], v[70:71], 0, s[4:5]
	global_load_lds_dwordx4 v78, s[60:61]
	s_mov_b32 m0, s70
	s_mov_b64 s[4:5], 0x680
	global_load_lds_dwordx4 v[88:89], off
	s_mov_b32 m0, s71
	s_nop 0
	global_load_lds_dwordx4 v84, s[60:61]
	ds_read_b128 v[88:91], v79 offset:32768
	ds_read_b128 v[92:95], v81 offset:49152
	ds_read_b128 v[96:99], v81 offset:53248
	s_waitcnt lgkmcnt(0)
	v_mfma_f32_32x32x16_bf16 v[48:63], v[88:91], v[92:95], v[48:63]
	s_mov_b32 m0, s84
	v_mfma_f32_32x32x16_bf16 v[32:47], v[88:91], v[96:99], v[32:47]
	ds_read_b128 v[88:91], v79 offset:36864
	s_waitcnt lgkmcnt(0)
	v_mfma_f32_32x32x16_bf16 v[16:31], v[88:91], v[92:95], v[16:31]
	v_mfma_f32_32x32x16_bf16 v[0:15], v[88:91], v[96:99], v[0:15]
	ds_read_b128 v[88:91], v80 offset:32768
	ds_read_b128 v[92:95], v83 offset:49152
	ds_read_b128 v[96:99], v83 offset:53248
	s_waitcnt lgkmcnt(0)
	v_mfma_f32_32x32x16_bf16 v[48:63], v[88:91], v[92:95], v[48:63]
	v_mfma_f32_32x32x16_bf16 v[32:47], v[88:91], v[96:99], v[32:47]
	ds_read_b128 v[88:91], v80 offset:36864
	s_waitcnt lgkmcnt(0)
	v_mfma_f32_32x32x16_bf16 v[16:31], v[88:91], v[92:95], v[16:31]
	v_mfma_f32_32x32x16_bf16 v[0:15], v[88:91], v[96:99], v[0:15]
	ds_read_b128 v[88:91], v82 offset:32768
	ds_read_b128 v[92:95], v85 offset:49152
	ds_read_b128 v[96:99], v85 offset:53248
	s_waitcnt lgkmcnt(0)
	v_mfma_f32_32x32x16_bf16 v[48:63], v[88:91], v[92:95], v[48:63]
	v_mfma_f32_32x32x16_bf16 v[32:47], v[88:91], v[96:99], v[32:47]
	ds_read_b128 v[88:91], v82 offset:36864
	s_waitcnt lgkmcnt(0)
	v_mfma_f32_32x32x16_bf16 v[16:31], v[88:91], v[92:95], v[16:31]
	v_mfma_f32_32x32x16_bf16 v[0:15], v[88:91], v[96:99], v[0:15]
	ds_read_b128 v[88:91], v86 offset:32768
	ds_read_b128 v[92:95], v87 offset:49152
	ds_read_b128 v[96:99], v87 offset:53248
	s_waitcnt lgkmcnt(0)
	v_mfma_f32_32x32x16_bf16 v[48:63], v[88:91], v[92:95], v[48:63]
	v_mfma_f32_32x32x16_bf16 v[32:47], v[88:91], v[96:99], v[32:47]
	ds_read_b128 v[88:91], v86 offset:36864
	s_waitcnt vmcnt(0)
	s_waitcnt vmcnt(0) lgkmcnt(0)
	s_barrier
; #define WAIT_V0() asm volatile("s_waitcnt vmcnt(0)" ::: "memory")
; DI void gemm_core(char* smem, int nk, const char* Ab, const char* Bb, const unsigned (&aoff)[4], const unsigned (&boff)[4],
;                   f32x16 (&acc)[2][2]) {
;     ...
;   auto stage = [&](int buf, int kt) __attribute__((always_inline)) {
;     const char* ak = Ab + kt * 128;
;     const char* bk = Bb + kt * 128;
;     char* sa = smem + buf * STAGE_B + w * 4096;
; #pragma unroll
;     for (int i = 0; i < 4; ++i) {
;       __builtin_amdgcn_global_load_lds((const unsigned*)(ak + aoff[i]), (unsigned*)(sa + i * 1024), 16, 0, 0);
;       __builtin_amdgcn_global_load_lds((const unsigned*)(bk + boff[i]), (unsigned*)(sa + 16384 + i * 1024), 16, 0, 0);
;     }
;   };
;     ...
;   for (int kt = 0; kt < nk; ++kt) {
;     const int cur = kt & 1;
;     if (kt + 1 < nk) stage(cur ^ 1, kt + 1);
;     const char* sb = smem + cur * STAGE_B;
; #pragma unroll
;     for (int ks = 0; ks < 4; ++ks) {
;       bf16x8 af[2], bfr[2];
; #pragma unroll
;       for (int mb = 0; mb < 2; ++mb) af[mb] = *(const bf16x8*)(sb + a_base + mb * 4096 + xo[ks]);
; #pragma unroll
;       for (int nb = 0; nb < 2; ++nb) bfr[nb] = *(const bf16x8*)(sb + b_base + nb * 4096 + xo[ks]);
; #pragma unroll
;       for (int mb = 0; mb < 2; ++mb)
; #pragma unroll
;         for (int nb = 0; nb < 2; ++nb)
;           acc[mb][nb] = __builtin_amdgcn_mfma_f32_32x32x16_bf16(af[mb], bfr[nb], acc[mb][nb], 0, 0, 0);
;     }
;     WAIT_V0();
;     __syncthreads();
;   }
	v_mfma_f32_32x32x16_bf16 v[16:31], v[88:91], v[92:95], v[16:31]
	v_mfma_f32_32x32x16_bf16 v[0:15], v[88:91], v[96:99], v[0:15]
	v_lshl_add_u64 v[88:89], v[64:65], 0, s[4:5]
	global_load_lds_dwordx4 v[88:89], off
	s_mov_b32 m0, s85
	v_lshl_add_u64 v[88:89], v[66:67], 0, s[4:5]
	global_load_lds_dwordx4 v76, s[62:63]
	s_mov_b32 m0, s86
	s_nop 0
	global_load_lds_dwordx4 v[88:89], off
	s_mov_b32 m0, s87
	v_lshl_add_u64 v[88:89], v[68:69], 0, s[4:5]
	global_load_lds_dwordx4 v77, s[62:63]
	s_mov_b32 m0, s88
	s_nop 0
	global_load_lds_dwordx4 v[88:89], off
	s_mov_b32 m0, s89
	v_lshl_add_u64 v[88:89], v[70:71], 0, s[4:5]
	global_load_lds_dwordx4 v78, s[62:63]
	s_mov_b32 m0, s90
	s_mov_b64 s[4:5], 0x700
	global_load_lds_dwordx4 v[88:89], off
	s_mov_b32 m0, s91
	s_nop 0
	global_load_lds_dwordx4 v84, s[62:63]
	ds_read_b128 v[88:91], v79
	ds_read_b128 v[92:95], v81 offset:16384
	ds_read_b128 v[96:99], v81 offset:20480
	s_waitcnt lgkmcnt(0)
	v_mfma_f32_32x32x16_bf16 v[48:63], v[88:91], v[92:95], v[48:63]
	s_mov_b32 m0, s18
	v_mfma_f32_32x32x16_bf16 v[32:47], v[88:91], v[96:99], v[32:47]
	ds_read_b128 v[88:91], v79 offset:4096
	s_waitcnt lgkmcnt(0)
	v_mfma_f32_32x32x16_bf16 v[16:31], v[88:91], v[92:95], v[16:31]
	v_mfma_f32_32x32x16_bf16 v[0:15], v[88:91], v[96:99], v[0:15]
	ds_read_b128 v[88:91], v80
	ds_read_b128 v[92:95], v83 offset:16384
	ds_read_b128 v[96:99], v83 offset:20480
	s_waitcnt lgkmcnt(0)
	v_mfma_f32_32x32x16_bf16 v[48:63], v[88:91], v[92:95], v[48:63]
	v_mfma_f32_32x32x16_bf16 v[32:47], v[88:91], v[96:99], v[32:47]
	ds_read_b128 v[88:91], v80 offset:4096
	s_waitcnt lgkmcnt(0)
	v_mfma_f32_32x32x16_bf16 v[16:31], v[88:91], v[92:95], v[16:31]
	v_mfma_f32_32x32x16_bf16 v[0:15], v[88:91], v[96:99], v[0:15]
	ds_read_b128 v[88:91], v82
	ds_read_b128 v[92:95], v85 offset:16384
	ds_read_b128 v[96:99], v85 offset:20480
	s_waitcnt lgkmcnt(0)
	v_mfma_f32_32x32x16_bf16 v[48:63], v[88:91], v[92:95], v[48:63]
	v_mfma_f32_32x32x16_bf16 v[32:47], v[88:91], v[96:99], v[32:47]
	ds_read_b128 v[88:91], v82 offset:4096
	s_waitcnt lgkmcnt(0)
	v_mfma_f32_32x32x16_bf16 v[16:31], v[88:91], v[92:95], v[16:31]
	v_mfma_f32_32x32x16_bf16 v[0:15], v[88:91], v[96:99], v[0:15]
	ds_read_b128 v[88:91], v86
	ds_read_b128 v[92:95], v87 offset:16384
	ds_read_b128 v[96:99], v87 offset:20480
	s_waitcnt lgkmcnt(0)
	v_mfma_f32_32x32x16_bf16 v[48:63], v[88:91], v[92:95], v[48:63]
	v_mfma_f32_32x32x16_bf16 v[32:47], v[88:91], v[96:99], v[32:47]
	ds_read_b128 v[88:91], v86 offset:4096
	s_waitcnt vmcnt(0)
	s_waitcnt vmcnt(0) lgkmcnt(0)
	s_barrier
	v_mfma_f32_32x32x16_bf16 v[16:31], v[88:91], v[92:95], v[16:31]
	v_mfma_f32_32x32x16_bf16 v[0:15], v[88:91], v[96:99], v[0:15]
	v_lshl_add_u64 v[88:89], v[64:65], 0, s[4:5]
	global_load_lds_dwordx4 v[88:89], off
	s_mov_b32 m0, s19
	v_lshl_add_u64 v[88:89], v[66:67], 0, s[4:5]
	global_load_lds_dwordx4 v76, s[64:65]
	s_mov_b32 m0, s22
	s_nop 0
	global_load_lds_dwordx4 v[88:89], off
	s_mov_b32 m0, s23
	v_lshl_add_u64 v[88:89], v[68:69], 0, s[4:5]
	global_load_lds_dwordx4 v77, s[64:65]
	s_mov_b32 m0, s29
	s_nop 0
	global_load_lds_dwordx4 v[88:89], off
	s_mov_b32 m0, s69
	v_lshl_add_u64 v[88:89], v[70:71], 0, s[4:5]
	global_load_lds_dwordx4 v78, s[64:65]
	s_mov_b32 m0, s70
	s_mov_b64 s[4:5], 0x780
	global_load_lds_dwordx4 v[88:89], off
	s_mov_b32 m0, s71
	v_lshl_add_u64 v[64:65], v[64:65], 0, s[4:5]
	global_load_lds_dwordx4 v84, s[64:65]
	ds_read_b128 v[88:91], v79 offset:32768
	ds_read_b128 v[92:95], v81 offset:49152
	ds_read_b128 v[96:99], v81 offset:53248
	s_waitcnt lgkmcnt(0)
	v_mfma_f32_32x32x16_bf16 v[48:63], v[88:91], v[92:95], v[48:63]
	s_mov_b32 m0, s84
	s_movk_i32 s4, 0x4000
	v_mfma_f32_32x32x16_bf16 v[32:47], v[88:91], v[96:99], v[32:47]
	ds_read_b128 v[88:91], v79 offset:36864
	s_waitcnt lgkmcnt(0)
	v_mfma_f32_32x32x16_bf16 v[16:31], v[88:91], v[92:95], v[16:31]
	v_mfma_f32_32x32x16_bf16 v[0:15], v[88:91], v[96:99], v[0:15]
	ds_read_b128 v[88:91], v80 offset:32768
	ds_read_b128 v[92:95], v83 offset:49152
	ds_read_b128 v[96:99], v83 offset:53248
	s_waitcnt lgkmcnt(0)
	v_mfma_f32_32x32x16_bf16 v[48:63], v[88:91], v[92:95], v[48:63]
	v_mfma_f32_32x32x16_bf16 v[32:47], v[88:91], v[96:99], v[32:47]
	ds_read_b128 v[88:91], v80 offset:36864
	s_waitcnt lgkmcnt(0)
	v_mfma_f32_32x32x16_bf16 v[16:31], v[88:91], v[92:95], v[16:31]
	v_mfma_f32_32x32x16_bf16 v[0:15], v[88:91], v[96:99], v[0:15]
	ds_read_b128 v[88:91], v82 offset:32768
	ds_read_b128 v[92:95], v85 offset:49152
	ds_read_b128 v[96:99], v85 offset:53248
	s_waitcnt lgkmcnt(0)
	v_mfma_f32_32x32x16_bf16 v[48:63], v[88:91], v[92:95], v[48:63]
	v_mfma_f32_32x32x16_bf16 v[32:47], v[88:91], v[96:99], v[32:47]
	ds_read_b128 v[88:91], v82 offset:36864
	s_waitcnt lgkmcnt(0)
	v_mfma_f32_32x32x16_bf16 v[16:31], v[88:91], v[92:95], v[16:31]
	v_mfma_f32_32x32x16_bf16 v[0:15], v[88:91], v[96:99], v[0:15]
	ds_read_b128 v[88:91], v86 offset:32768
	ds_read_b128 v[92:95], v87 offset:49152
	ds_read_b128 v[96:99], v87 offset:53248
	s_waitcnt lgkmcnt(0)
	v_mfma_f32_32x32x16_bf16 v[48:63], v[88:91], v[92:95], v[48:63]
	v_mfma_f32_32x32x16_bf16 v[32:47], v[88:91], v[96:99], v[32:47]
	ds_read_b128 v[88:91], v86 offset:36864
	s_waitcnt vmcnt(0)
	s_waitcnt vmcnt(0) lgkmcnt(0)
	s_barrier
; #define WAIT_V0() asm volatile("s_waitcnt vmcnt(0)" ::: "memory")
; DI void gemm_core(char* smem, int nk, const char* Ab, const char* Bb, const unsigned (&aoff)[4], const unsigned (&boff)[4],
;                   f32x16 (&acc)[2][2]) {
;     ...
;   auto stage = [&](int buf, int kt) __attribute__((always_inline)) {
;     const char* ak = Ab + kt * 128;
;     const char* bk = Bb + kt * 128;
;     char* sa = smem + buf * STAGE_B + w * 4096;
; #pragma unroll
;     for (int i = 0; i < 4; ++i) {
;       __builtin_amdgcn_global_load_lds((const unsigned*)(ak + aoff[i]), (unsigned*)(sa + i * 1024), 16, 0, 0);
;       __builtin_amdgcn_global_load_lds((const unsigned*)(bk + boff[i]), (unsigned*)(sa + 16384 + i * 1024), 16, 0, 0);
;     }
;   };
;     ...
;   for (int kt = 0; kt < nk; ++kt) {
;     const int cur = kt & 1;
;     if (kt + 1 < nk) stage(cur ^ 1, kt + 1);
;     const char* sb = smem + cur * STAGE_B;
; #pragma unroll
;     for (int ks = 0; ks < 4; ++ks) {
;       bf16x8 af[2], bfr[2];
; #pragma unroll
;       for (int mb = 0; mb < 2; ++mb) af[mb] = *(const bf16x8*)(sb + a_base + mb * 4096 + xo[ks]);
; #pragma unroll
;       for (int nb = 0; nb < 2; ++nb) bfr[nb] = *(const bf16x8*)(sb + b_base + nb * 4096 + xo[ks]);
; #pragma unroll
;       for (int mb = 0; mb < 2; ++mb)
; #pragma unroll
;         for (int nb = 0; nb < 2; ++nb)
;           acc[mb][nb] = __builtin_amdgcn_mfma_f32_32x32x16_bf16(af[mb], bfr[nb], acc[mb][nb], 0, 0, 0);
;     }
;     WAIT_V0();
;     __syncthreads();
;   }
	global_load_lds_dwordx4 v[64:65], off
	s_mov_b32 m0, s85
	v_lshl_add_u64 v[64:65], v[66:67], 0, s[6:7]
	global_load_lds_dwordx4 v76, s[66:67]
	s_mov_b32 m0, s86
	v_mfma_f32_32x32x16_bf16 v[16:31], v[88:91], v[92:95], v[16:31]
	global_load_lds_dwordx4 v[64:65], off
	s_mov_b32 m0, s87
	v_lshl_add_u64 v[64:65], v[68:69], 0, s[6:7]
	global_load_lds_dwordx4 v77, s[66:67]
	s_mov_b32 m0, s88
	v_mfma_f32_32x32x16_bf16 v[0:15], v[88:91], v[96:99], v[0:15]
	global_load_lds_dwordx4 v[64:65], off
	s_mov_b32 m0, s89
	v_lshl_add_u64 v[64:65], v[70:71], 0, s[6:7]
	global_load_lds_dwordx4 v78, s[66:67]
	s_mov_b32 m0, s90
	v_readlane_b32 s86, v254, 58
	global_load_lds_dwordx4 v[64:65], off
	s_mov_b32 m0, s91
	v_readlane_b32 s87, v254, 59
	global_load_lds_dwordx4 v84, s[66:67]
	ds_read_b128 v[64:67], v79
	ds_read_b128 v[68:71], v81 offset:16384
	ds_read_b128 v[88:91], v81 offset:20480
	s_waitcnt lgkmcnt(0)
	v_mfma_f32_32x32x16_bf16 v[48:63], v[64:67], v[68:71], v[48:63]
	v_mfma_f32_32x32x16_bf16 v[32:47], v[64:67], v[88:91], v[32:47]
	ds_read_b128 v[64:67], v79 offset:4096
	s_waitcnt lgkmcnt(0)
	v_mfma_f32_32x32x16_bf16 v[16:31], v[64:67], v[68:71], v[16:31]
	v_mfma_f32_32x32x16_bf16 v[0:15], v[64:67], v[88:91], v[0:15]
	ds_read_b128 v[64:67], v80
	ds_read_b128 v[68:71], v83 offset:16384
	ds_read_b128 v[88:91], v83 offset:20480
	s_waitcnt lgkmcnt(0)
	v_mfma_f32_32x32x16_bf16 v[48:63], v[64:67], v[68:71], v[48:63]
	v_mfma_f32_32x32x16_bf16 v[32:47], v[64:67], v[88:91], v[32:47]
	ds_read_b128 v[64:67], v80 offset:4096
	s_waitcnt lgkmcnt(0)
	v_mfma_f32_32x32x16_bf16 v[16:31], v[64:67], v[68:71], v[16:31]
	v_mfma_f32_32x32x16_bf16 v[0:15], v[64:67], v[88:91], v[0:15]
	ds_read_b128 v[64:67], v82
	ds_read_b128 v[68:71], v85 offset:16384
	ds_read_b128 v[88:91], v85 offset:20480
	s_waitcnt lgkmcnt(0)
	v_mfma_f32_32x32x16_bf16 v[48:63], v[64:67], v[68:71], v[48:63]
	v_mfma_f32_32x32x16_bf16 v[32:47], v[64:67], v[88:91], v[32:47]
	ds_read_b128 v[64:67], v82 offset:4096
	s_waitcnt lgkmcnt(0)
	v_mfma_f32_32x32x16_bf16 v[16:31], v[64:67], v[68:71], v[16:31]
	v_mfma_f32_32x32x16_bf16 v[0:15], v[64:67], v[88:91], v[0:15]
	ds_read_b128 v[64:67], v86
	ds_read_b128 v[68:71], v87 offset:16384
	ds_read_b128 v[88:91], v87 offset:20480
	s_waitcnt lgkmcnt(0)
	v_mfma_f32_32x32x16_bf16 v[48:63], v[64:67], v[68:71], v[48:63]
	v_mfma_f32_32x32x16_bf16 v[32:47], v[64:67], v[88:91], v[32:47]
	ds_read_b128 v[64:67], v86 offset:4096
	s_waitcnt vmcnt(0)
	s_waitcnt vmcnt(0) lgkmcnt(0)
	s_barrier
	v_mfma_f32_32x32x16_bf16 v[16:31], v[64:67], v[68:71], v[16:31]
	v_mfma_f32_32x32x16_bf16 v[0:15], v[64:67], v[88:91], v[0:15]
	ds_read_b128 v[64:67], v79 offset:32768
	ds_read_b128 v[68:71], v81 offset:49152
	ds_read_b128 v[88:91], v81 offset:53248
	s_waitcnt lgkmcnt(1)
	v_mfma_f32_32x32x16_bf16 v[48:63], v[64:67], v[68:71], v[48:63]
	s_waitcnt lgkmcnt(0)
	v_mfma_f32_32x32x16_bf16 v[32:47], v[64:67], v[88:91], v[32:47]
	ds_read_b128 v[64:67], v79 offset:36864
	s_waitcnt lgkmcnt(0)
	v_mfma_f32_32x32x16_bf16 v[16:31], v[64:67], v[68:71], v[16:31]
	v_mfma_f32_32x32x16_bf16 v[0:15], v[64:67], v[88:91], v[0:15]
	ds_read_b128 v[64:67], v80 offset:32768
	ds_read_b128 v[68:71], v83 offset:49152
	ds_read_b128 v[76:79], v83 offset:53248
	s_waitcnt lgkmcnt(1)
	v_mfma_f32_32x32x16_bf16 v[48:63], v[64:67], v[68:71], v[48:63]
	s_waitcnt lgkmcnt(0)
	v_mfma_f32_32x32x16_bf16 v[32:47], v[64:67], v[76:79], v[32:47]
	ds_read_b128 v[64:67], v80 offset:36864
	s_waitcnt lgkmcnt(0)
	v_mfma_f32_32x32x16_bf16 v[16:31], v[64:67], v[68:71], v[16:31]
	v_mfma_f32_32x32x16_bf16 v[0:15], v[64:67], v[76:79], v[0:15]
	ds_read_b128 v[64:67], v82 offset:32768
	ds_read_b128 v[68:71], v85 offset:49152
	ds_read_b128 v[76:79], v85 offset:53248
	s_waitcnt lgkmcnt(1)
	v_mfma_f32_32x32x16_bf16 v[48:63], v[64:67], v[68:71], v[48:63]
	s_waitcnt lgkmcnt(0)
	v_mfma_f32_32x32x16_bf16 v[32:47], v[64:67], v[76:79], v[32:47]
	ds_read_b128 v[64:67], v82 offset:36864
	s_waitcnt lgkmcnt(0)
	v_mfma_f32_32x32x16_bf16 v[16:31], v[64:67], v[68:71], v[16:31]
	ds_read_b128 v[68:71], v87 offset:53248
	ds_read_b128 v[80:83], v87 offset:49152
	ds_read_b128 v[88:91], v86 offset:36864
	ds_read_b128 v[84:87], v86 offset:32768
	s_waitcnt vmcnt(0)
	s_waitcnt lgkmcnt(0)
	s_barrier
; DI int ltid() { int t = threadIdx.x; asm volatile("" : "+v"(t)); return t; }
; template <class F>
; DI void epi_foreach(const f32x16 (&acc)[2][2], F f) {
;   const int lane = ltid() & 63, w = ltid() >> 6;
;   const int wm = w >> 1, wn = w & 1;
; #pragma unroll
;   for (int mb = 0; mb < 2; ++mb)
; #pragma unroll
;     for (int nb = 0; nb < 2; ++nb)
; #pragma unroll
;       for (int r = 0; r < 16; ++r) {
;         const int row = wm * 64 + mb * 32 + (r & 3) + 8 * (r >> 2) + 4 * (lane >> 5);
;         const int col = wn * 64 + nb * 32 + (lane & 31);
;         f(row, col, acc[mb][nb][r]);
;         if ((r & 7) == 7) __builtin_amdgcn_sched_barrier(0);
;       }
; DI void phase_up(const Params& P, int layer, char* smem) {
;     ...
;     epi_foreach(acc, [&](int row, int col, float v) __attribute__((always_inline)) { Cs[row * 136 + col] = f2bf(v); });
;     __syncthreads();
;     {
;       const int col = tid & 63, rb = tid >> 6;
;       const int cv = nt * 64 + col, cg_ = DFF + nt * 64 + col;
;       const float w0v = cw[cv], w1v = cw[5632 + cv], w2v = cw[2 * 5632 + cv], bv = cb[cv];
;       const float w0g = cw[cg_], w1g = cw[5632 + cg_], w2g = cw[2 * 5632 + cg_], bgt = cb[cg_];
	v_mfma_f32_32x32x16_bf16 v[48:63], v[84:87], v[80:83], v[48:63]
	v_mfma_f32_32x32x16_bf16 v[0:15], v[64:67], v[76:79], v[0:15]
	v_mov_b32_e32 v64, v161
	v_mov_b32_e32 v65, v161
	v_lshrrev_b32_e32 v67, 3, v64
	v_and_b32_e32 v67, 4, v67
	v_lshrrev_b32_e32 v66, 1, v65
	v_and_b32_e32 v64, 31, v64
	v_and_or_b32 v64, v65, 64, v64
	v_and_or_b32 v65, v66, s3, v67
	v_mul_lo_u32 v65, v65, s97
	s_nop 1
	v_cvt_pk_bf16_f32 v48, v48, s0
	v_lshl_add_u32 v64, v64, 1, v65
	ds_write_b16 v64, v48
	v_cvt_pk_bf16_f32 v48, v49, s0
	ds_write_b16 v64, v48 offset:272
	v_cvt_pk_bf16_f32 v48, v50, s0
	ds_write_b16 v64, v48 offset:544
	v_cvt_pk_bf16_f32 v48, v51, s0
	ds_write_b16 v64, v48 offset:816
	v_cvt_pk_bf16_f32 v48, v52, s0
	ds_write_b16 v64, v48 offset:2176
	v_cvt_pk_bf16_f32 v48, v53, s0
	ds_write_b16 v64, v48 offset:2448
	v_cvt_pk_bf16_f32 v48, v54, s0
	ds_write_b16 v64, v48 offset:2720
	v_cvt_pk_bf16_f32 v48, v55, s0
	v_mfma_f32_32x32x16_bf16 v[32:47], v[84:87], v[68:71], v[32:47]
	ds_write_b16 v64, v48 offset:2992
	v_mfma_f32_32x32x16_bf16 v[16:31], v[88:91], v[80:83], v[16:31]
	v_mfma_f32_32x32x16_bf16 v[0:15], v[88:91], v[68:71], v[0:15]
	v_cvt_pk_bf16_f32 v48, v56, s0
	ds_write_b16 v64, v48 offset:4352
	v_cvt_pk_bf16_f32 v48, v57, s0
	ds_write_b16 v64, v48 offset:4624
	v_cvt_pk_bf16_f32 v48, v58, s0
	ds_write_b16 v64, v48 offset:4896
	v_cvt_pk_bf16_f32 v48, v59, s0
	ds_write_b16 v64, v48 offset:5168
	v_cvt_pk_bf16_f32 v48, v60, s0
	ds_write_b16 v64, v48 offset:6528
	v_cvt_pk_bf16_f32 v48, v61, s0
	ds_write_b16 v64, v48 offset:6800
	v_cvt_pk_bf16_f32 v48, v62, s0
	ds_write_b16 v64, v48 offset:7072
	v_cvt_pk_bf16_f32 v48, v63, s0
	ds_write_b16 v64, v48 offset:7344
	v_cvt_pk_bf16_f32 v32, v32, s0
	ds_write_b16 v64, v32 offset:64
	v_cvt_pk_bf16_f32 v32, v33, s0
	ds_write_b16 v64, v32 offset:336
	v_cvt_pk_bf16_f32 v32, v34, s0
	ds_write_b16 v64, v32 offset:608
	v_cvt_pk_bf16_f32 v32, v35, s0
	ds_write_b16 v64, v32 offset:880
	v_cvt_pk_bf16_f32 v32, v36, s0
	ds_write_b16 v64, v32 offset:2240
	v_cvt_pk_bf16_f32 v32, v37, s0
	ds_write_b16 v64, v32 offset:2512
	v_cvt_pk_bf16_f32 v32, v38, s0
	ds_write_b16 v64, v32 offset:2784
	v_cvt_pk_bf16_f32 v32, v39, s0
	ds_write_b16 v64, v32 offset:3056
	v_cvt_pk_bf16_f32 v32, v40, s0
	ds_write_b16 v64, v32 offset:4416
	v_cvt_pk_bf16_f32 v32, v41, s0
	ds_write_b16 v64, v32 offset:4688
	v_cvt_pk_bf16_f32 v32, v42, s0
	ds_write_b16 v64, v32 offset:4960
	v_cvt_pk_bf16_f32 v32, v43, s0
	ds_write_b16 v64, v32 offset:5232
	v_cvt_pk_bf16_f32 v32, v44, s0
	ds_write_b16 v64, v32 offset:6592
	v_cvt_pk_bf16_f32 v32, v45, s0
	ds_write_b16 v64, v32 offset:6864
	v_cvt_pk_bf16_f32 v32, v46, s0
	ds_write_b16 v64, v32 offset:7136
	v_cvt_pk_bf16_f32 v32, v47, s0
	ds_write_b16 v64, v32 offset:7408
	v_cvt_pk_bf16_f32 v16, v16, s0
	ds_write_b16 v64, v16 offset:8704
	v_cvt_pk_bf16_f32 v16, v17, s0
	ds_write_b16 v64, v16 offset:8976
	v_cvt_pk_bf16_f32 v16, v18, s0
	ds_write_b16 v64, v16 offset:9248
	v_cvt_pk_bf16_f32 v16, v19, s0
	ds_write_b16 v64, v16 offset:9520
	v_cvt_pk_bf16_f32 v16, v20, s0
	ds_write_b16 v64, v16 offset:10880
	v_cvt_pk_bf16_f32 v16, v21, s0
	ds_write_b16 v64, v16 offset:11152
	v_cvt_pk_bf16_f32 v16, v22, s0
	ds_write_b16 v64, v16 offset:11424
	v_cvt_pk_bf16_f32 v16, v23, s0
	ds_write_b16 v64, v16 offset:11696
	v_cvt_pk_bf16_f32 v16, v24, s0
	ds_write_b16 v64, v16 offset:13056
	v_cvt_pk_bf16_f32 v16, v25, s0
	ds_write_b16 v64, v16 offset:13328
	v_cvt_pk_bf16_f32 v16, v26, s0
	ds_write_b16 v64, v16 offset:13600
	v_cvt_pk_bf16_f32 v16, v27, s0
	ds_write_b16 v64, v16 offset:13872
	v_cvt_pk_bf16_f32 v16, v28, s0
	ds_write_b16 v64, v16 offset:15232
	v_cvt_pk_bf16_f32 v16, v29, s0
	ds_write_b16 v64, v16 offset:15504
	v_cvt_pk_bf16_f32 v16, v30, s0
	ds_write_b16 v64, v16 offset:15776
	v_cvt_pk_bf16_f32 v16, v31, s0
	ds_write_b16 v64, v16 offset:16048
	v_cvt_pk_bf16_f32 v0, v0, s0
	ds_write_b16 v64, v0 offset:8768
	v_cvt_pk_bf16_f32 v0, v1, s0
	ds_write_b16 v64, v0 offset:9040
	v_cvt_pk_bf16_f32 v0, v2, s0
	ds_write_b16 v64, v0 offset:9312
	v_cvt_pk_bf16_f32 v0, v3, s0
	ds_write_b16 v64, v0 offset:9584
	v_cvt_pk_bf16_f32 v0, v4, s0
	ds_write_b16 v64, v0 offset:10944
	v_cvt_pk_bf16_f32 v0, v5, s0
	ds_write_b16 v64, v0 offset:11216
	v_cvt_pk_bf16_f32 v0, v6, s0
	ds_write_b16 v64, v0 offset:11488
	v_cvt_pk_bf16_f32 v0, v7, s0
	ds_write_b16 v64, v0 offset:11760
	v_cvt_pk_bf16_f32 v0, v8, s0
	ds_write_b16 v64, v0 offset:13120
	v_cvt_pk_bf16_f32 v0, v9, s0
	ds_write_b16 v64, v0 offset:13392
	v_cvt_pk_bf16_f32 v0, v10, s0
	ds_write_b16 v64, v0 offset:13664
	v_cvt_pk_bf16_f32 v0, v11, s0
	ds_write_b16 v64, v0 offset:13936
	v_cvt_pk_bf16_f32 v0, v12, s0
	ds_write_b16 v64, v0 offset:15296
	v_cvt_pk_bf16_f32 v0, v13, s0
	ds_write_b16 v64, v0 offset:15568
	v_cvt_pk_bf16_f32 v0, v14, s0
	ds_write_b16 v64, v0 offset:15840
	v_cvt_pk_bf16_f32 v0, v15, s0
	ds_write_b16 v64, v0 offset:16112
	s_waitcnt lgkmcnt(0)
	s_barrier
	s_and_saveexec_b64 s[18:19], s[40:41]
	s_mov_b32 s3, 0xb000
	s_cbranch_execz .LBB0_24
	v_add_u32_e32 v136, s21, v74
	v_lshlrev_b64 v[4:5], 2, v[136:137]
	v_lshl_add_u64 v[8:9], s[10:11], 0, v[4:5]
	v_or_b32_e32 v10, s21, v72
	v_lshlrev_b32_e32 v126, 1, v10
	v_lshl_add_u64 v[2:3], s[12:13], 0, v[4:5]
	v_add_co_u32_e32 v4, vcc, 0xb000, v8
	v_ashrrev_i32_e32 v11, 31, v10
	s_nop 0
	v_addc_co_u32_e32 v5, vcc, 0, v9, vcc
	v_lshl_add_u64 v[0:1], v[10:11], 1, s[86:87]
	v_add_co_u32_e32 v6, vcc, 0x5000, v8
	v_lshlrev_b64 v[10:11], 2, v[10:11]
	s_nop 0
	v_addc_co_u32_e32 v7, vcc, 0, v9, vcc
	v_lshl_add_u64 v[12:13], s[12:13], 0, v[10:11]
	v_lshl_add_u64 v[10:11], s[10:11], 0, v[10:11]
	global_load_dword v3, v[2:3], off
	s_mulk_i32 s20, 0x7e
	global_load_dword v5, v[4:5], off
	s_nop 0
	global_load_dword v7, v[6:7], off offset:2048
	s_nop 0
	global_load_dword v9, v[8:9], off
	s_mul_i32 s21, s68, 0x7a
	global_load_dword v2, v[12:13], off
	v_add_co_u32_e32 v12, vcc, s3, v10
	s_sub_i32 s29, s20, s21
	s_nop 0
	v_addc_co_u32_e32 v13, vcc, 0, v11, vcc
	global_load_dword v4, v[12:13], off
	v_add_co_u32_e32 v12, vcc, 0x5000, v10
	s_mov_b64 s[20:21], 0
	s_nop 0
	v_addc_co_u32_e32 v13, vcc, 0, v11, vcc
	global_load_dword v6, v[12:13], off offset:2048
	global_load_dword v8, v[10:11], off
	v_mov_b32_e32 v11, v73
	v_mul_u32_u24_e32 v10, 0x110, v73
	v_mov_b32_e32 v128, 0
	v_mov_b32_e32 v129, 0
	v_mov_b32_e32 v130, 0
	v_mov_b32_e32 v131, 0
	v_mov_b32_e32 v132, 0
	v_mov_b32_e32 v133, 0
	v_mov_b32_e32 v134, 0
	v_mov_b32_e32 v135, 0
	s_waitcnt vmcnt(0)
	v_readfirstlane_b32 s22, v73
	v_add_u32_e32 v10, v75, v10
	v_add_u32_e32 v127, 0x1600, v126
	s_lshl_b32 s22, s22, 1
	s_add_i32 s23, s29, s22
	s_mul_hi_i32 s21, s23, 0x1600
	s_mul_i32 s20, s23, 0x1600
	s_add_u32 s20, s20, s86
	s_addc_u32 s21, s21, s87
	s_branch .LBB0_28
; DI float bf2f(unsigned short u) { return __uint_as_float(((unsigned)u) << 16); }
; DI void phase_up(const Params& P, int layer, char* smem) {
;     ...
;       for (int r = 2 + rb; r < 128; r += 4) {
;         const int tb = tb0 + r;
;         if (tb < S_) {
;           const float val = bv + w0v * bf2f(Cs[(r - 2) * 136 + col]) + w1v * bf2f(Cs[(r - 1) * 136 + col]) + w2v * bf2f(Cs[r * 136 + col]);
;           const float gat = bgt + w0g * bf2f(Cs[(r - 2) * 136 + 64 + col]) + w1g * bf2f(Cs[(r - 1) * 136 + 64 + col]) + w2g * bf2f(Cs[r * 136 + 64 + col]);
;           const float a = gat / (1.f + __expf(-gat)) * val;
;           ACT[(size_t)(b * S_ + tb) * DFF + cv] = f2bf(a);
;         }
;       }
.LBB0_28:
	ds_read_u16_d16_hi v128, v10
	ds_read_u16_d16_hi v129, v10 offset:128
	ds_read_u16_d16_hi v130, v10 offset:272
	ds_read_u16_d16_hi v131, v10 offset:400
	ds_read_u16_d16_hi v132, v10 offset:544
	ds_read_u16_d16_hi v133, v10 offset:672
	ds_read_u16_d16_hi v134, v10 offset:816
	ds_read_u16_d16_hi v135, v10 offset:944
	s_waitcnt lgkmcnt(6)
	v_pk_fma_f32 v[118:119], v[8:9], v[128:129], v[2:3]
	s_waitcnt lgkmcnt(4)
	v_pk_fma_f32 v[118:119], v[6:7], v[130:131], v[118:119]
	v_pk_fma_f32 v[120:121], v[8:9], v[130:131], v[2:3]
	s_waitcnt lgkmcnt(2)
	v_pk_fma_f32 v[118:119], v[4:5], v[132:133], v[118:119]
	v_pk_fma_f32 v[120:121], v[6:7], v[132:133], v[120:121]
	s_waitcnt lgkmcnt(0)
	v_mul_f32_e32 v12, 0xbfb8aa3b, v119
	v_pk_fma_f32 v[120:121], v[4:5], v[134:135], v[120:121]
	v_exp_f32_e32 v12, v12
	s_nop 0
	v_mul_f32_e32 v18, 0xbfb8aa3b, v121
	v_add_f32_e32 v12, 1.0, v12
	v_exp_f32_e32 v18, v18
	v_div_scale_f32 v13, s[68:69], v12, v12, v119
	v_add_f32_e32 v18, 1.0, v18
	v_rcp_f32_e32 v14, v13
	v_div_scale_f32 v19, s[68:69], v18, v18, v121
	v_fma_f32 v15, -v13, v14, 1.0
	v_rcp_f32_e32 v122, v19
	v_fmac_f32_e32 v14, v15, v14
	v_div_scale_f32 v15, vcc, v119, v12, v119
	v_fma_f32 v123, -v19, v122, 1.0
	v_mul_f32_e32 v16, v15, v14
	v_fmac_f32_e32 v122, v123, v122
	v_fma_f32 v17, -v13, v16, v15
	v_fmac_f32_e32 v16, v17, v14
	v_fma_f32 v13, -v13, v16, v15
	v_div_fmas_f32 v13, v13, v14, v16
	v_div_scale_f32 v123, vcc, v121, v18, v121
	v_div_fixup_f32 v119, v13, v12, v119
	v_mul_f32_e32 v124, v123, v122
	v_mul_f32_e32 v118, v118, v119
	v_fma_f32 v125, -v19, v124, v123
	v_cvt_pk_bf16_f32 v12, v118, s0
	v_fmac_f32_e32 v124, v125, v122
	v_fma_f32 v19, -v19, v124, v123
	v_div_fmas_f32 v19, v19, v122, v124
	v_div_fixup_f32 v121, v19, v18, v121
	v_mul_f32_e32 v120, v120, v121
	v_cvt_pk_bf16_f32 v18, v120, s0
	s_add_i32 s23, s28, s22
	s_cmp_lt_i32 s23, s4
	s_cbranch_scc0 .Lconv_skipA
	global_store_short v126, v12, s[20:21]
